# WKV7 prompt scan: v operand read 4 steps per ds_read from a transposed f32 image written by the loader waves; y select moved into a DPP gap; loader waits only for its LRU operand loads
# speedup vs baseline: 1.1138x; 1.0050x over previous
; #define LAS __attribute__((address_space(3)))
; __device__ __forceinline__ int make_tid(int wv) { int lane_v; asm volatile("v_mbcnt_lo_u32_b32 %0, -1, 0\n\tv_mbcnt_hi_u32_b32 %0, -1, %0" : "=v"(lane_v)); return wv * 64 + lane_v; }
; #define WKV_BAR() do { asm volatile("s_waitcnt lgkmcnt(0)" ::: "memory"); __builtin_amdgcn_s_barrier(); asm volatile("" ::: "memory"); } while (0)
; __device__ __forceinline__ void scan_wkv_prompt(PP P, int l, LAS unsigned char* lds, const Ids I) {
;     const int tid = make_tid(I.wv), wave = __builtin_amdgcn_readfirstlane(tid >> 6), lane = tid & 63, rowl = lane >> 4, kseg = lane & 15; unsigned char* ws = P->ws;
;     const bf16_t* arr = (const bf16_t*)(ws + WS_R2); const unsigned AS = (unsigned)MT * 512u; bf16_t* ymix = (bf16_t*)(ws + WS_HB); float* out = P->out;
;     LAS float* buf = (LAS float*)lds;
;     LAS float* ybuf = buf + 2 * 32 * 336;
;     LAS unsigned char* raw = lds + 90112;
;     ...
;     for (int u = BID; u < 256; u += NB) {
;         const int bh = u >> 2, rg = u & 3, b = bh >> 3, h = bh & 7; const unsigned rowbase = (unsigned)b * 2048u;
;         if (wave >= 4) {
;             const int lw = wave - 4, lsl = lane >> 3, part = lane & 7, ls = lw * 8 + lsl;
;             const bf16_t* g5[5] = {arr + A_R * AS, arr + A_EW * AS, arr + A_KF * AS, arr + A_KK * AS, arr + A_BB * AS};
;     ...
;             float S0 = 0.f, S1 = 0.f, S2 = 0.f, S3 = 0.f; f32x4 rp = (f32x4){0.f, 0.f, 0.f, 0.f};
;     ...
;             float dmy = 0.f, dmy2;
;     ...
;             __builtin_amdgcn_s_setprio(3);
; #pragma unroll 1
;             for (int c = 0; c < 64; ++c) {
;                 WKV_BAR();
;                 const LAS float* bp = buf + (c & 1) * (32 * 336) + kseg * 4; LAS float* yb = ybuf + (c & 1) * 512; const int vo = 320 + wave * 4 + rowl - kseg * 4;
;     ...
;                 const unsigned ap = (unsigned)(size_t)bp, apv = (unsigned)(size_t)(bp + vo);
.LBB0_754:
	s_nop 0
	v_mbcnt_lo_u32_b32 v1, -1, 0
	v_mbcnt_hi_u32_b32 v1, -1, v1
	v_writelane_b32 v254, s42, 52
	v_add_u32_e32 v0, s62, v1
	s_and_b64 vcc, exec, s[42:43]
	v_readfirstlane_b32 s0, v0
	v_writelane_b32 v254, s43, 53
	s_cbranch_vccz .LBB0_805
	v_readlane_b32 s1, v254, 41
	s_lshl_b32 s3, s1, 6
	v_writelane_b32 v254, s3, 59
	s_lshl_b32 s1, s1, 12
	s_ashr_i32 s3, s0, 6
	s_cmp_lt_i32 s3, 4
	v_writelane_b32 v254, s1, 63
	s_cselect_b64 s[0:1], -1, 0
	v_writelane_b32 v254, s0, 55
	v_and_b32_e32 v18, 15, v1
	v_lshlrev_b32_e32 v8, 4, v18
	v_writelane_b32 v254, s1, 56
	s_lshl_b32 s0, s3, 4
	s_waitcnt lgkmcnt(0)
	v_readlane_b32 s12, v254, 2
	s_add_i32 s44, s0, s12
	s_load_dwordx2 s[0:1], s[88:89], 0x140
	v_mov_b32_e32 v9, v145
	s_lshl_b32 s85, s3, 2
	s_add_i32 s3, s3, -4
	s_lshl_b32 s57, s3, 8
	s_waitcnt lgkmcnt(0)
	v_lshl_add_u64 v[2:3], s[0:1], 0, v[8:9]
	s_mov_b64 s[0:1], 0x423c000
	v_lshl_add_u64 v[10:11], v[2:3], 0, s[0:1]
	s_lshl_b32 s0, s3, 10
	s_add_i32 s1, s0, 0
	v_bfe_u32 v2, v1, 3, 3
	s_add_i32 s6, s1, 0x16000
	v_and_b32_e32 v4, 63, v1
	v_bfe_u32 v13, v1, 4, 2
	v_and_b32_e32 v3, 7, v1
	v_lshl_or_b32 v9, s3, 3, v2
	v_writelane_b32 v255, s6, 0
	s_add_i32 s3, s57, 0
	v_lshlrev_b32_e32 v1, 4, v1
	v_lshlrev_b32_e32 v20, 3, v3
	v_writelane_b32 v255, s3, 1
	s_add_i32 s6, s3, 0x1b000
	v_and_b32_e32 v25, 16, v1
	v_bfe_u32 v26, v0, 4, 4
	v_lshlrev_b32_e32 v1, 6, v9
	s_movk_i32 s3, 0x540
	v_writelane_b32 v255, s6, 2
	v_add3_u32 v28, s12, v1, v20
	v_cmp_eq_u32_e64 s[12:13], 15, v26
	v_lshlrev_b32_e32 v22, 4, v4
	v_mul_lo_u32 v4, v9, s3
	v_lshlrev_b32_e32 v24, 5, v2
	v_and_b32_e32 v0, 0xff, v0
	v_readlane_b32 s3, v254, 3
	v_writelane_b32 v255, s12, 3
	v_lshlrev_b32_e32 v5, 2, v13
	v_lshlrev_b32_e32 v6, 5, v3
	v_add_u32_e32 v2, s6, v24
	v_cmp_eq_u32_e32 vcc, 0, v26
	v_lshl_add_u32 v30, v0, 3, s3
	v_writelane_b32 v255, s13, 4
	v_readlane_b32 s12, v254, 4
	v_lshlrev_b32_e32 v0, 6, v18
	v_or_b32_e32 v19, s85, v13
	v_cmp_eq_u32_e64 s[4:5], 0, v18
	v_lshlrev_b32_e32 v12, 1, v3
	v_add_u32_e32 v21, 32, v9
	v_add3_u32 v23, 0, v4, v6
	v_lshlrev_b32_e32 v124, 10, v3
	v_lshl_add_u32 v124, v9, 2, v124
	v_add_u32_e32 v124, 0x21400, v124
	v_cmp_gt_u32_e64 s[6:7], 2, v3
	v_lshlrev_b32_e32 v27, 7, v26
	v_cmp_lt_i32_e64 s[8:9], 0, v9
	v_add_u32_e32 v29, 64, v9
	v_add3_u32 v31, s12, v1, v20
	v_add_u32_e32 v32, 0x7e0, v9
	v_cmp_eq_u32_e64 s[12:13], 1, v18
	v_cmp_eq_u32_e64 s[14:15], 2, v18
	v_cmp_eq_u32_e64 s[16:17], 3, v18
	v_cmp_eq_u32_e64 s[18:19], 4, v18
	v_cmp_eq_u32_e64 s[20:21], 5, v18
	v_cmp_eq_u32_e64 s[22:23], 6, v18
	v_cmp_eq_u32_e64 s[24:25], 7, v18
	v_cmp_eq_u32_e64 s[26:27], 8, v18
	v_cmp_eq_u32_e64 s[28:29], 9, v18
	v_cmp_eq_u32_e64 s[30:31], 10, v18
	v_cmp_eq_u32_e64 s[34:35], 11, v18
	v_cmp_eq_u32_e64 s[36:37], 12, v18
	v_cmp_eq_u32_e64 s[38:39], 13, v18
	v_cmp_eq_u32_e64 s[40:41], 14, v18
	v_cmp_eq_u32_e64 s[42:43], 15, v18
	v_add3_u32 v33, s44, v5, v0
	v_lshl_add_u32 v34, v18, 3, s3
	v_add_u32_e32 v35, v2, v25
	s_xor_b64 s[68:69], vcc, -1
	s_mov_b32 s3, s93
	s_branch .LBB0_758

; #define LAS __attribute__((address_space(3)))
; __device__ __forceinline__ void scan_wkv_prompt(PP P, int l, LAS unsigned char* lds, const Ids I) {
;     ...
;             for (int c = 0; c < 64; ++c) {
;                 WKV_BAR();
;                 const LAS float* bp = buf + (c & 1) * (32 * 336) + kseg * 4; LAS float* yb = ybuf + (c & 1) * 512; const int vo = 320 + wave * 4 + rowl - kseg * 4;
;     ...
;                 const unsigned ap = (unsigned)(size_t)bp, apv = (unsigned)(size_t)(bp + vo);
;                 f32x4 r4, w4, k4, a4, b4, nr4, nw4, nk4, na4, nb4; float vv, nvv;
;                 WKV_LDS6(r4, w4, k4, a4, b4, vv, "", 0);
;                 WKV_LDS6(nr4, nw4, nk4, na4, nb4, nvv, "", 1344);
;                 float ykeep = 0.f;
; #pragma unroll
;                 for (int s = 0; s < 32; ++s) {
;                     f32x4 mr4 = r4, mw4 = w4, mk4 = k4, ma4 = a4, mb4 = b4; float mvv = vv;
;                     if (s < 30) { WKV_LDS6(mr4, mw4, mk4, ma4, mb4, mvv, "s_waitcnt lgkmcnt(6)\n\t", (s + 2) * 1344); }
;                     else if (s == 30) asm volatile("s_waitcnt lgkmcnt(6)" ::: "memory");
;                     else asm volatile("s_waitcnt lgkmcnt(0)" ::: "memory");
;                     __builtin_amdgcn_sched_barrier(0);
;                     float sum, y, p1, q1, t0, t1, t2, t3;
;                     asm volatile(
;                         "v_mul_f32 %0, %8, %12\n\t"  "v_mul_f32 %1, %8, %16\n\t"
;                         "v_fma_f32 %0, %9, %13, %0\n\t"  "v_fma_f32 %1, %9, %17, %1\n\t"
;                         "v_mul_f32 %2, %10, %14\n\t"  "v_mul_f32 %3, %10, %18\n\t"
;                         "v_fma_f32 %2, %11, %15, %2\n\t"  "v_fma_f32 %3, %11, %19, %3\n\t"
;                         "v_add_f32 %0, %0, %2\n\t"  "v_add_f32 %1, %1, %3\n\t"
;                         "v_mul_f32 %4, %20, %21\n\t"  "v_mul_f32 %5, %20, %22\n\t"
;                         DPPA("%0", "quad_perm:[1,0,3,2]") DPPA("%1", "quad_perm:[1,0,3,2]")
;                         "v_mul_f32 %6, %20, %23\n\t"
;                         DPPA("%0", "quad_perm:[2,3,0,1]") DPPA("%1", "quad_perm:[2,3,0,1]")
;                         "v_mul_f32 %7, %20, %24\n\t"
;                         DPPA("%0", "row_half_mirror") DPPA("%1", "row_half_mirror")
;                         "s_nop 0\n\t"
;                         DPPA("%0", "row_mirror") DPPA("%1", "row_mirror")
.LBB0_760:
	s_and_b32 s45, s44, 1
	s_mul_i32 s50, s45, 0xa800
	s_add_i32 s50, s50, 0
	s_lshl_b32 s51, s85, 2
	v_add_u32_e32 v2, s50, v8
	s_add_i32 s50, s50, s51
	s_lshl_b32 s51, s45, 11
	s_add_i32 s51, s51, 0x21400
	s_waitcnt lgkmcnt(0)
	s_barrier
	v_lshl_add_u32 v126, v19, 7, s51
	ds_read_b128 v[40:43], v2 offset:256
	ds_read_b128 v[44:47], v2 offset:512
	ds_read_b128 v[48:51], v2 offset:768
	ds_read_b128 v[52:55], v2 offset:1024
	ds_read_b128 v[128:131], v126 offset:0
	ds_read_b128 v[60:63], v2 offset:0
	ds_read_b128 v[64:67], v2 offset:1600
	ds_read_b128 v[68:71], v2 offset:1856
	ds_read_b128 v[72:75], v2 offset:2112
	ds_read_b128 v[76:79], v2 offset:2368
	s_waitcnt lgkmcnt(5)
	ds_read_b128 v[84:87], v2 offset:1344
	ds_read_b128 v[88:91], v2 offset:2944
	ds_read_b128 v[92:95], v2 offset:3200
	ds_read_b128 v[96:99], v2 offset:3456
	ds_read_b128 v[100:103], v2 offset:3712
	v_pk_mul_f32 v[108:109], v[0:1], v[48:49]
	v_pk_mul_f32 v[110:111], v[0:1], v[4:5]
	v_pk_fma_f32 v[108:109], v[14:15], v[50:51], v[108:109]
	v_pk_fma_f32 v[110:111], v[14:15], v[6:7], v[110:111]
	v_add_f32_e32 v116, v108, v109
	v_add_f32_e32 v117, v110, v111
	v_pk_mul_f32 v[112:113], v[128:129], v[44:45] op_sel_hi:[0,1]
	v_add_f32_dpp v116, v116, v116 quad_perm:[1,0,3,2] row_mask:0xf bank_mask:0xf bound_ctrl:1
	v_add_f32_dpp v117, v117, v117 quad_perm:[1,0,3,2] row_mask:0xf bank_mask:0xf bound_ctrl:1
	v_pk_mul_f32 v[114:115], v[128:129], v[46:47] op_sel_hi:[0,1]
	v_add_f32_dpp v116, v116, v116 quad_perm:[2,3,0,1] row_mask:0xf bank_mask:0xf bound_ctrl:1
	v_add_f32_dpp v117, v117, v117 quad_perm:[2,3,0,1] row_mask:0xf bank_mask:0xf bound_ctrl:1
	s_nop 0
	v_add_f32_dpp v116, v116, v116 row_half_mirror row_mask:0xf bank_mask:0xf bound_ctrl:1
	v_add_f32_dpp v117, v117, v117 row_half_mirror row_mask:0xf bank_mask:0xf bound_ctrl:1
	s_nop 0
	v_add_f32_dpp v116, v116, v116 row_mirror row_mask:0xf bank_mask:0xf bound_ctrl:1
	v_add_f32_dpp v117, v117, v117 row_mirror row_mask:0xf bank_mask:0xf bound_ctrl:1
	v_pk_fma_f32 v[112:113], v[116:117], v[52:53], v[112:113] op_sel_hi:[0,1,1] neg_lo:[1,0,0] neg_hi:[1,0,0]
	v_pk_fma_f32 v[114:115], v[116:117], v[54:55], v[114:115] op_sel_hi:[0,1,1] neg_lo:[1,0,0] neg_hi:[1,0,0]
	v_pk_fma_f32 v[0:1], v[0:1], v[40:41], v[112:113]
	v_pk_fma_f32 v[14:15], v[14:15], v[42:43], v[114:115]
	s_waitcnt lgkmcnt(5)
	ds_read_b128 v[36:39], v2 offset:2688
	ds_read_b128 v[40:43], v2 offset:4288
	ds_read_b128 v[44:47], v2 offset:4544
	ds_read_b128 v[48:51], v2 offset:4800
	ds_read_b128 v[52:55], v2 offset:5056
	v_pk_mul_f32 v[108:109], v[0:1], v[72:73]
	v_pk_mul_f32 v[110:111], v[0:1], v[60:61]
	v_pk_fma_f32 v[108:109], v[14:15], v[74:75], v[108:109]
	v_pk_fma_f32 v[110:111], v[14:15], v[62:63], v[110:111]
	v_add_f32_e32 v116, v108, v109
	v_add_f32_e32 v137, v110, v111
	v_pk_mul_f32 v[112:113], v[128:129], v[68:69] op_sel:[1,0] op_sel_hi:[1,1]
	v_add_f32_dpp v116, v116, v116 quad_perm:[1,0,3,2] row_mask:0xf bank_mask:0xf bound_ctrl:1
	v_add_f32_dpp v137, v137, v137 quad_perm:[1,0,3,2] row_mask:0xf bank_mask:0xf bound_ctrl:1
	v_pk_mul_f32 v[114:115], v[128:129], v[70:71] op_sel:[1,0] op_sel_hi:[1,1]
	v_add_f32_dpp v116, v116, v116 quad_perm:[2,3,0,1] row_mask:0xf bank_mask:0xf bound_ctrl:1
	v_add_f32_dpp v137, v137, v137 quad_perm:[2,3,0,1] row_mask:0xf bank_mask:0xf bound_ctrl:1
	v_cndmask_b32_e64 v118, v118, v117, s[4:5]
	v_add_f32_dpp v116, v116, v116 row_half_mirror row_mask:0xf bank_mask:0xf bound_ctrl:1
	v_add_f32_dpp v137, v137, v137 row_half_mirror row_mask:0xf bank_mask:0xf bound_ctrl:1
	s_nop 0
	v_add_f32_dpp v116, v116, v116 row_mirror row_mask:0xf bank_mask:0xf bound_ctrl:1
	v_add_f32_dpp v137, v137, v137 row_mirror row_mask:0xf bank_mask:0xf bound_ctrl:1
	v_pk_fma_f32 v[112:113], v[116:117], v[76:77], v[112:113] op_sel_hi:[0,1,1] neg_lo:[1,0,0] neg_hi:[1,0,0]
	v_pk_fma_f32 v[114:115], v[116:117], v[78:79], v[114:115] op_sel_hi:[0,1,1] neg_lo:[1,0,0] neg_hi:[1,0,0]
	v_pk_fma_f32 v[0:1], v[0:1], v[64:65], v[112:113]
	v_pk_fma_f32 v[14:15], v[14:15], v[66:67], v[114:115]
	s_waitcnt lgkmcnt(5)
	ds_read_b128 v[60:63], v2 offset:4032
	ds_read_b128 v[64:67], v2 offset:5632
	ds_read_b128 v[68:71], v2 offset:5888
	ds_read_b128 v[72:75], v2 offset:6144
	ds_read_b128 v[76:79], v2 offset:6400
	ds_read_b128 v[132:135], v126 offset:16
	v_pk_mul_f32 v[108:109], v[0:1], v[96:97]
	v_pk_mul_f32 v[110:111], v[0:1], v[84:85]
	v_pk_fma_f32 v[108:109], v[14:15], v[98:99], v[108:109]
	v_pk_fma_f32 v[110:111], v[14:15], v[86:87], v[110:111]
	v_add_f32_e32 v116, v108, v109
	v_add_f32_e32 v117, v110, v111
	v_pk_mul_f32 v[112:113], v[130:131], v[92:93] op_sel_hi:[0,1]
	v_add_f32_dpp v116, v116, v116 quad_perm:[1,0,3,2] row_mask:0xf bank_mask:0xf bound_ctrl:1
	v_add_f32_dpp v117, v117, v117 quad_perm:[1,0,3,2] row_mask:0xf bank_mask:0xf bound_ctrl:1
	v_pk_mul_f32 v[114:115], v[130:131], v[94:95] op_sel_hi:[0,1]
	v_add_f32_dpp v116, v116, v116 quad_perm:[2,3,0,1] row_mask:0xf bank_mask:0xf bound_ctrl:1
	v_add_f32_dpp v117, v117, v117 quad_perm:[2,3,0,1] row_mask:0xf bank_mask:0xf bound_ctrl:1
	v_cndmask_b32_e64 v118, v118, v137, s[12:13]
	v_add_f32_dpp v116, v116, v116 row_half_mirror row_mask:0xf bank_mask:0xf bound_ctrl:1
	v_add_f32_dpp v117, v117, v117 row_half_mirror row_mask:0xf bank_mask:0xf bound_ctrl:1
	s_nop 0
	v_add_f32_dpp v116, v116, v116 row_mirror row_mask:0xf bank_mask:0xf bound_ctrl:1
	v_add_f32_dpp v117, v117, v117 row_mirror row_mask:0xf bank_mask:0xf bound_ctrl:1
	v_pk_fma_f32 v[112:113], v[116:117], v[100:101], v[112:113] op_sel_hi:[0,1,1] neg_lo:[1,0,0] neg_hi:[1,0,0]
	v_pk_fma_f32 v[114:115], v[116:117], v[102:103], v[114:115] op_sel_hi:[0,1,1] neg_lo:[1,0,0] neg_hi:[1,0,0]
	v_pk_fma_f32 v[0:1], v[0:1], v[88:89], v[112:113]
	v_pk_fma_f32 v[14:15], v[14:15], v[90:91], v[114:115]
	s_waitcnt lgkmcnt(6)
; __device__ __forceinline__ void scan_wkv_prompt(PP P, int l, LAS unsigned char* lds, const Ids I) {
;     ...
;                 for (int s = 0; s < 32; ++s) {
;                     f32x4 mr4 = r4, mw4 = w4, mk4 = k4, ma4 = a4, mb4 = b4; float mvv = vv;
;                     if (s < 30) { WKV_LDS6(mr4, mw4, mk4, ma4, mb4, mvv, "s_waitcnt lgkmcnt(6)\n\t", (s + 2) * 1344); }
;                     else if (s == 30) asm volatile("s_waitcnt lgkmcnt(6)" ::: "memory");
;                     else asm volatile("s_waitcnt lgkmcnt(0)" ::: "memory");
;                     __builtin_amdgcn_sched_barrier(0);
;                     float sum, y, p1, q1, t0, t1, t2, t3;
;                     asm volatile(
;                         "v_mul_f32 %0, %8, %12\n\t"  "v_mul_f32 %1, %8, %16\n\t"
;                         "v_fma_f32 %0, %9, %13, %0\n\t"  "v_fma_f32 %1, %9, %17, %1\n\t"
;                         "v_mul_f32 %2, %10, %14\n\t"  "v_mul_f32 %3, %10, %18\n\t"
;                         "v_fma_f32 %2, %11, %15, %2\n\t"  "v_fma_f32 %3, %11, %19, %3\n\t"
;                         "v_add_f32 %0, %0, %2\n\t"  "v_add_f32 %1, %1, %3\n\t"
;                         "v_mul_f32 %4, %20, %21\n\t"  "v_mul_f32 %5, %20, %22\n\t"
;                         DPPA("%0", "quad_perm:[1,0,3,2]") DPPA("%1", "quad_perm:[1,0,3,2]")
;                         "v_mul_f32 %6, %20, %23\n\t"
;                         DPPA("%0", "quad_perm:[2,3,0,1]") DPPA("%1", "quad_perm:[2,3,0,1]")
;                         "v_mul_f32 %7, %20, %24\n\t"
;                         DPPA("%0", "row_half_mirror") DPPA("%1", "row_half_mirror")
;                         "s_nop 0\n\t"
;                         DPPA("%0", "row_mirror") DPPA("%1", "row_mirror")
;                         : "=&v"(sum), "=&v"(y), "=&v"(p1), "=&v"(q1), "=&v"(t0), "=&v"(t1), "=&v"(t2), "=&v"(t3)
;                         : "v"(S0), "v"(S1), "v"(S2), "v"(S3), "v"(a4[0]), "v"(a4[1]), "v"(a4[2]), "v"(a4[3]), "v"(rp[0]), "v"(rp[1]), "v"(rp[2]), "v"(rp[3]),
;                           "v"(vv), "v"(k4[0]), "v"(k4[1]), "v"(k4[2]), "v"(k4[3]));
;                     asm volatile(
;                         "v_fma_f32 %4, -%8, %9, %4\n\t"  "v_fma_f32 %5, -%8, %10, %5\n\t"  "v_fma_f32 %6, -%8, %11, %6\n\t"  "v_fma_f32 %7, -%8, %12, %7\n\t"
	ds_read_b128 v[84:87], v2 offset:5376
	ds_read_b128 v[88:91], v2 offset:6976
	ds_read_b128 v[92:95], v2 offset:7232
	ds_read_b128 v[96:99], v2 offset:7488
	ds_read_b128 v[100:103], v2 offset:7744
	v_pk_mul_f32 v[108:109], v[0:1], v[48:49]
	v_pk_mul_f32 v[110:111], v[0:1], v[36:37]
	v_pk_fma_f32 v[108:109], v[14:15], v[50:51], v[108:109]
	v_pk_fma_f32 v[110:111], v[14:15], v[38:39], v[110:111]
	v_add_f32_e32 v116, v108, v109
	v_add_f32_e32 v137, v110, v111
	v_pk_mul_f32 v[112:113], v[130:131], v[44:45] op_sel:[1,0] op_sel_hi:[1,1]
	v_add_f32_dpp v116, v116, v116 quad_perm:[1,0,3,2] row_mask:0xf bank_mask:0xf bound_ctrl:1
	v_add_f32_dpp v137, v137, v137 quad_perm:[1,0,3,2] row_mask:0xf bank_mask:0xf bound_ctrl:1
	v_pk_mul_f32 v[114:115], v[130:131], v[46:47] op_sel:[1,0] op_sel_hi:[1,1]
	v_add_f32_dpp v116, v116, v116 quad_perm:[2,3,0,1] row_mask:0xf bank_mask:0xf bound_ctrl:1
	v_add_f32_dpp v137, v137, v137 quad_perm:[2,3,0,1] row_mask:0xf bank_mask:0xf bound_ctrl:1
	v_cndmask_b32_e64 v118, v118, v117, s[14:15]
	v_add_f32_dpp v116, v116, v116 row_half_mirror row_mask:0xf bank_mask:0xf bound_ctrl:1
	v_add_f32_dpp v137, v137, v137 row_half_mirror row_mask:0xf bank_mask:0xf bound_ctrl:1
	s_nop 0
	v_add_f32_dpp v116, v116, v116 row_mirror row_mask:0xf bank_mask:0xf bound_ctrl:1
	v_add_f32_dpp v137, v137, v137 row_mirror row_mask:0xf bank_mask:0xf bound_ctrl:1
	v_pk_fma_f32 v[112:113], v[116:117], v[52:53], v[112:113] op_sel_hi:[0,1,1] neg_lo:[1,0,0] neg_hi:[1,0,0]
	v_pk_fma_f32 v[114:115], v[116:117], v[54:55], v[114:115] op_sel_hi:[0,1,1] neg_lo:[1,0,0] neg_hi:[1,0,0]
	v_pk_fma_f32 v[0:1], v[0:1], v[40:41], v[112:113]
	v_pk_fma_f32 v[14:15], v[14:15], v[42:43], v[114:115]
	s_waitcnt lgkmcnt(5)
	ds_read_b128 v[36:39], v2 offset:6720
	ds_read_b128 v[40:43], v2 offset:8320
	ds_read_b128 v[44:47], v2 offset:8576
	ds_read_b128 v[48:51], v2 offset:8832
	ds_read_b128 v[52:55], v2 offset:9088
	v_pk_mul_f32 v[108:109], v[0:1], v[72:73]
	v_pk_mul_f32 v[110:111], v[0:1], v[60:61]
	v_pk_fma_f32 v[108:109], v[14:15], v[74:75], v[108:109]
	v_pk_fma_f32 v[110:111], v[14:15], v[62:63], v[110:111]
	v_add_f32_e32 v116, v108, v109
	v_add_f32_e32 v117, v110, v111
	v_pk_mul_f32 v[112:113], v[132:133], v[68:69] op_sel_hi:[0,1]
	v_add_f32_dpp v116, v116, v116 quad_perm:[1,0,3,2] row_mask:0xf bank_mask:0xf bound_ctrl:1
	v_add_f32_dpp v117, v117, v117 quad_perm:[1,0,3,2] row_mask:0xf bank_mask:0xf bound_ctrl:1
	v_pk_mul_f32 v[114:115], v[132:133], v[70:71] op_sel_hi:[0,1]
	v_add_f32_dpp v116, v116, v116 quad_perm:[2,3,0,1] row_mask:0xf bank_mask:0xf bound_ctrl:1
	v_add_f32_dpp v117, v117, v117 quad_perm:[2,3,0,1] row_mask:0xf bank_mask:0xf bound_ctrl:1
	v_cndmask_b32_e64 v118, v118, v137, s[16:17]
	v_add_f32_dpp v116, v116, v116 row_half_mirror row_mask:0xf bank_mask:0xf bound_ctrl:1
	v_add_f32_dpp v117, v117, v117 row_half_mirror row_mask:0xf bank_mask:0xf bound_ctrl:1
	s_nop 0
	v_add_f32_dpp v116, v116, v116 row_mirror row_mask:0xf bank_mask:0xf bound_ctrl:1
	v_add_f32_dpp v117, v117, v117 row_mirror row_mask:0xf bank_mask:0xf bound_ctrl:1
	v_pk_fma_f32 v[112:113], v[116:117], v[76:77], v[112:113] op_sel_hi:[0,1,1] neg_lo:[1,0,0] neg_hi:[1,0,0]
	v_pk_fma_f32 v[114:115], v[116:117], v[78:79], v[114:115] op_sel_hi:[0,1,1] neg_lo:[1,0,0] neg_hi:[1,0,0]
	v_pk_fma_f32 v[0:1], v[0:1], v[64:65], v[112:113]
	v_pk_fma_f32 v[14:15], v[14:15], v[66:67], v[114:115]
	s_waitcnt lgkmcnt(5)
	ds_read_b128 v[60:63], v2 offset:8064
	ds_read_b128 v[64:67], v2 offset:9664
	ds_read_b128 v[68:71], v2 offset:9920
	ds_read_b128 v[72:75], v2 offset:10176
	ds_read_b128 v[76:79], v2 offset:10432
	v_pk_mul_f32 v[108:109], v[0:1], v[96:97]
	v_pk_mul_f32 v[110:111], v[0:1], v[84:85]
	v_pk_fma_f32 v[108:109], v[14:15], v[98:99], v[108:109]
	v_pk_fma_f32 v[110:111], v[14:15], v[86:87], v[110:111]
	v_add_f32_e32 v116, v108, v109
	v_add_f32_e32 v137, v110, v111
	v_pk_mul_f32 v[112:113], v[132:133], v[92:93] op_sel:[1,0] op_sel_hi:[1,1]
	v_add_f32_dpp v116, v116, v116 quad_perm:[1,0,3,2] row_mask:0xf bank_mask:0xf bound_ctrl:1
	v_add_f32_dpp v137, v137, v137 quad_perm:[1,0,3,2] row_mask:0xf bank_mask:0xf bound_ctrl:1
	v_pk_mul_f32 v[114:115], v[132:133], v[94:95] op_sel:[1,0] op_sel_hi:[1,1]
	v_add_f32_dpp v116, v116, v116 quad_perm:[2,3,0,1] row_mask:0xf bank_mask:0xf bound_ctrl:1
	v_add_f32_dpp v137, v137, v137 quad_perm:[2,3,0,1] row_mask:0xf bank_mask:0xf bound_ctrl:1
	v_cndmask_b32_e64 v118, v118, v117, s[18:19]
	v_add_f32_dpp v116, v116, v116 row_half_mirror row_mask:0xf bank_mask:0xf bound_ctrl:1
	v_add_f32_dpp v137, v137, v137 row_half_mirror row_mask:0xf bank_mask:0xf bound_ctrl:1
	s_nop 0
	v_add_f32_dpp v116, v116, v116 row_mirror row_mask:0xf bank_mask:0xf bound_ctrl:1
	v_add_f32_dpp v137, v137, v137 row_mirror row_mask:0xf bank_mask:0xf bound_ctrl:1
	v_pk_fma_f32 v[112:113], v[116:117], v[100:101], v[112:113] op_sel_hi:[0,1,1] neg_lo:[1,0,0] neg_hi:[1,0,0]
	v_pk_fma_f32 v[114:115], v[116:117], v[102:103], v[114:115] op_sel_hi:[0,1,1] neg_lo:[1,0,0] neg_hi:[1,0,0]
	v_pk_fma_f32 v[0:1], v[0:1], v[88:89], v[112:113]
	v_pk_fma_f32 v[14:15], v[14:15], v[90:91], v[114:115]
	s_waitcnt lgkmcnt(5)
; __device__ __forceinline__ void scan_wkv_prompt(PP P, int l, LAS unsigned char* lds, const Ids I) {
;     ...
;                 for (int s = 0; s < 32; ++s) {
;                     f32x4 mr4 = r4, mw4 = w4, mk4 = k4, ma4 = a4, mb4 = b4; float mvv = vv;
;                     if (s < 30) { WKV_LDS6(mr4, mw4, mk4, ma4, mb4, mvv, "s_waitcnt lgkmcnt(6)\n\t", (s + 2) * 1344); }
;                     else if (s == 30) asm volatile("s_waitcnt lgkmcnt(6)" ::: "memory");
;                     else asm volatile("s_waitcnt lgkmcnt(0)" ::: "memory");
;                     __builtin_amdgcn_sched_barrier(0);
;                     float sum, y, p1, q1, t0, t1, t2, t3;
;                     asm volatile(
;                         "v_mul_f32 %0, %8, %12\n\t"  "v_mul_f32 %1, %8, %16\n\t"
;                         "v_fma_f32 %0, %9, %13, %0\n\t"  "v_fma_f32 %1, %9, %17, %1\n\t"
;                         "v_mul_f32 %2, %10, %14\n\t"  "v_mul_f32 %3, %10, %18\n\t"
;                         "v_fma_f32 %2, %11, %15, %2\n\t"  "v_fma_f32 %3, %11, %19, %3\n\t"
;                         "v_add_f32 %0, %0, %2\n\t"  "v_add_f32 %1, %1, %3\n\t"
;                         "v_mul_f32 %4, %20, %21\n\t"  "v_mul_f32 %5, %20, %22\n\t"
;                         DPPA("%0", "quad_perm:[1,0,3,2]") DPPA("%1", "quad_perm:[1,0,3,2]")
;                         "v_mul_f32 %6, %20, %23\n\t"
;                         DPPA("%0", "quad_perm:[2,3,0,1]") DPPA("%1", "quad_perm:[2,3,0,1]")
;                         "v_mul_f32 %7, %20, %24\n\t"
;                         DPPA("%0", "row_half_mirror") DPPA("%1", "row_half_mirror")
;                         "s_nop 0\n\t"
;                         DPPA("%0", "row_mirror") DPPA("%1", "row_mirror")
;                         : "=&v"(sum), "=&v"(y), "=&v"(p1), "=&v"(q1), "=&v"(t0), "=&v"(t1), "=&v"(t2), "=&v"(t3)
;                         : "v"(S0), "v"(S1), "v"(S2), "v"(S3), "v"(a4[0]), "v"(a4[1]), "v"(a4[2]), "v"(a4[3]), "v"(rp[0]), "v"(rp[1]), "v"(rp[2]), "v"(rp[3]),
;                           "v"(vv), "v"(k4[0]), "v"(k4[1]), "v"(k4[2]), "v"(k4[3]));
;                     asm volatile(
;                         "v_fma_f32 %4, -%8, %9, %4\n\t"  "v_fma_f32 %5, -%8, %10, %5\n\t"  "v_fma_f32 %6, -%8, %11, %6\n\t"  "v_fma_f32 %7, -%8, %12, %7\n\t"
	ds_read_b128 v[84:87], v2 offset:9408
	ds_read_b128 v[88:91], v2 offset:11008
	ds_read_b128 v[92:95], v2 offset:11264
	ds_read_b128 v[96:99], v2 offset:11520
	ds_read_b128 v[100:103], v2 offset:11776
	ds_read_b128 v[128:131], v126 offset:32
	v_pk_mul_f32 v[108:109], v[0:1], v[48:49]
	v_pk_mul_f32 v[110:111], v[0:1], v[36:37]
	v_pk_fma_f32 v[108:109], v[14:15], v[50:51], v[108:109]
	v_pk_fma_f32 v[110:111], v[14:15], v[38:39], v[110:111]
	v_add_f32_e32 v116, v108, v109
	v_add_f32_e32 v117, v110, v111
	v_pk_mul_f32 v[112:113], v[134:135], v[44:45] op_sel_hi:[0,1]
	v_add_f32_dpp v116, v116, v116 quad_perm:[1,0,3,2] row_mask:0xf bank_mask:0xf bound_ctrl:1
	v_add_f32_dpp v117, v117, v117 quad_perm:[1,0,3,2] row_mask:0xf bank_mask:0xf bound_ctrl:1
	v_pk_mul_f32 v[114:115], v[134:135], v[46:47] op_sel_hi:[0,1]
	v_add_f32_dpp v116, v116, v116 quad_perm:[2,3,0,1] row_mask:0xf bank_mask:0xf bound_ctrl:1
	v_add_f32_dpp v117, v117, v117 quad_perm:[2,3,0,1] row_mask:0xf bank_mask:0xf bound_ctrl:1
	v_cndmask_b32_e64 v118, v118, v137, s[20:21]
	v_add_f32_dpp v116, v116, v116 row_half_mirror row_mask:0xf bank_mask:0xf bound_ctrl:1
	v_add_f32_dpp v117, v117, v117 row_half_mirror row_mask:0xf bank_mask:0xf bound_ctrl:1
	s_nop 0
	v_add_f32_dpp v116, v116, v116 row_mirror row_mask:0xf bank_mask:0xf bound_ctrl:1
	v_add_f32_dpp v117, v117, v117 row_mirror row_mask:0xf bank_mask:0xf bound_ctrl:1
	v_pk_fma_f32 v[112:113], v[116:117], v[52:53], v[112:113] op_sel_hi:[0,1,1] neg_lo:[1,0,0] neg_hi:[1,0,0]
	v_pk_fma_f32 v[114:115], v[116:117], v[54:55], v[114:115] op_sel_hi:[0,1,1] neg_lo:[1,0,0] neg_hi:[1,0,0]
	v_pk_fma_f32 v[0:1], v[0:1], v[40:41], v[112:113]
	v_pk_fma_f32 v[14:15], v[14:15], v[42:43], v[114:115]
	s_waitcnt lgkmcnt(6)
	ds_read_b128 v[36:39], v2 offset:10752
	ds_read_b128 v[40:43], v2 offset:12352
	ds_read_b128 v[44:47], v2 offset:12608
	ds_read_b128 v[48:51], v2 offset:12864
	ds_read_b128 v[52:55], v2 offset:13120
	v_pk_mul_f32 v[108:109], v[0:1], v[72:73]
	v_pk_mul_f32 v[110:111], v[0:1], v[60:61]
	v_pk_fma_f32 v[108:109], v[14:15], v[74:75], v[108:109]
	v_pk_fma_f32 v[110:111], v[14:15], v[62:63], v[110:111]
	v_add_f32_e32 v116, v108, v109
	v_add_f32_e32 v137, v110, v111
	v_pk_mul_f32 v[112:113], v[134:135], v[68:69] op_sel:[1,0] op_sel_hi:[1,1]
	v_add_f32_dpp v116, v116, v116 quad_perm:[1,0,3,2] row_mask:0xf bank_mask:0xf bound_ctrl:1
	v_add_f32_dpp v137, v137, v137 quad_perm:[1,0,3,2] row_mask:0xf bank_mask:0xf bound_ctrl:1
	v_pk_mul_f32 v[114:115], v[134:135], v[70:71] op_sel:[1,0] op_sel_hi:[1,1]
	v_add_f32_dpp v116, v116, v116 quad_perm:[2,3,0,1] row_mask:0xf bank_mask:0xf bound_ctrl:1
	v_add_f32_dpp v137, v137, v137 quad_perm:[2,3,0,1] row_mask:0xf bank_mask:0xf bound_ctrl:1
	v_cndmask_b32_e64 v118, v118, v117, s[22:23]
	v_add_f32_dpp v116, v116, v116 row_half_mirror row_mask:0xf bank_mask:0xf bound_ctrl:1
	v_add_f32_dpp v137, v137, v137 row_half_mirror row_mask:0xf bank_mask:0xf bound_ctrl:1
	s_nop 0
	v_add_f32_dpp v116, v116, v116 row_mirror row_mask:0xf bank_mask:0xf bound_ctrl:1
	v_add_f32_dpp v137, v137, v137 row_mirror row_mask:0xf bank_mask:0xf bound_ctrl:1
	v_pk_fma_f32 v[112:113], v[116:117], v[76:77], v[112:113] op_sel_hi:[0,1,1] neg_lo:[1,0,0] neg_hi:[1,0,0]
	v_pk_fma_f32 v[114:115], v[116:117], v[78:79], v[114:115] op_sel_hi:[0,1,1] neg_lo:[1,0,0] neg_hi:[1,0,0]
	v_pk_fma_f32 v[0:1], v[0:1], v[64:65], v[112:113]
	v_pk_fma_f32 v[14:15], v[14:15], v[66:67], v[114:115]
	s_waitcnt lgkmcnt(5)
	ds_read_b128 v[60:63], v2 offset:12096
	ds_read_b128 v[64:67], v2 offset:13696
	ds_read_b128 v[68:71], v2 offset:13952
	ds_read_b128 v[72:75], v2 offset:14208
	ds_read_b128 v[76:79], v2 offset:14464
	v_pk_mul_f32 v[108:109], v[0:1], v[96:97]
	v_pk_mul_f32 v[110:111], v[0:1], v[84:85]
	v_pk_fma_f32 v[108:109], v[14:15], v[98:99], v[108:109]
	v_pk_fma_f32 v[110:111], v[14:15], v[86:87], v[110:111]
	v_add_f32_e32 v116, v108, v109
	v_add_f32_e32 v117, v110, v111
	v_pk_mul_f32 v[112:113], v[128:129], v[92:93] op_sel_hi:[0,1]
	v_add_f32_dpp v116, v116, v116 quad_perm:[1,0,3,2] row_mask:0xf bank_mask:0xf bound_ctrl:1
	v_add_f32_dpp v117, v117, v117 quad_perm:[1,0,3,2] row_mask:0xf bank_mask:0xf bound_ctrl:1
	v_pk_mul_f32 v[114:115], v[128:129], v[94:95] op_sel_hi:[0,1]
	v_add_f32_dpp v116, v116, v116 quad_perm:[2,3,0,1] row_mask:0xf bank_mask:0xf bound_ctrl:1
	v_add_f32_dpp v117, v117, v117 quad_perm:[2,3,0,1] row_mask:0xf bank_mask:0xf bound_ctrl:1
	v_cndmask_b32_e64 v118, v118, v137, s[24:25]
	v_add_f32_dpp v116, v116, v116 row_half_mirror row_mask:0xf bank_mask:0xf bound_ctrl:1
	v_add_f32_dpp v117, v117, v117 row_half_mirror row_mask:0xf bank_mask:0xf bound_ctrl:1
	s_nop 0
	v_add_f32_dpp v116, v116, v116 row_mirror row_mask:0xf bank_mask:0xf bound_ctrl:1
	v_add_f32_dpp v117, v117, v117 row_mirror row_mask:0xf bank_mask:0xf bound_ctrl:1
	v_pk_fma_f32 v[112:113], v[116:117], v[100:101], v[112:113] op_sel_hi:[0,1,1] neg_lo:[1,0,0] neg_hi:[1,0,0]
	v_pk_fma_f32 v[114:115], v[116:117], v[102:103], v[114:115] op_sel_hi:[0,1,1] neg_lo:[1,0,0] neg_hi:[1,0,0]
	v_pk_fma_f32 v[0:1], v[0:1], v[88:89], v[112:113]
	v_pk_fma_f32 v[14:15], v[14:15], v[90:91], v[114:115]
	s_waitcnt lgkmcnt(5)
; __device__ __forceinline__ void scan_wkv_prompt(PP P, int l, LAS unsigned char* lds, const Ids I) {
;     ...
;                 for (int s = 0; s < 32; ++s) {
;                     f32x4 mr4 = r4, mw4 = w4, mk4 = k4, ma4 = a4, mb4 = b4; float mvv = vv;
;                     if (s < 30) { WKV_LDS6(mr4, mw4, mk4, ma4, mb4, mvv, "s_waitcnt lgkmcnt(6)\n\t", (s + 2) * 1344); }
;                     else if (s == 30) asm volatile("s_waitcnt lgkmcnt(6)" ::: "memory");
;                     else asm volatile("s_waitcnt lgkmcnt(0)" ::: "memory");
;                     __builtin_amdgcn_sched_barrier(0);
;                     float sum, y, p1, q1, t0, t1, t2, t3;
;                     asm volatile(
;                         "v_mul_f32 %0, %8, %12\n\t"  "v_mul_f32 %1, %8, %16\n\t"
;                         "v_fma_f32 %0, %9, %13, %0\n\t"  "v_fma_f32 %1, %9, %17, %1\n\t"
;                         "v_mul_f32 %2, %10, %14\n\t"  "v_mul_f32 %3, %10, %18\n\t"
;                         "v_fma_f32 %2, %11, %15, %2\n\t"  "v_fma_f32 %3, %11, %19, %3\n\t"
;                         "v_add_f32 %0, %0, %2\n\t"  "v_add_f32 %1, %1, %3\n\t"
;                         "v_mul_f32 %4, %20, %21\n\t"  "v_mul_f32 %5, %20, %22\n\t"
;                         DPPA("%0", "quad_perm:[1,0,3,2]") DPPA("%1", "quad_perm:[1,0,3,2]")
;                         "v_mul_f32 %6, %20, %23\n\t"
;                         DPPA("%0", "quad_perm:[2,3,0,1]") DPPA("%1", "quad_perm:[2,3,0,1]")
;                         "v_mul_f32 %7, %20, %24\n\t"
;                         DPPA("%0", "row_half_mirror") DPPA("%1", "row_half_mirror")
;                         "s_nop 0\n\t"
;                         DPPA("%0", "row_mirror") DPPA("%1", "row_mirror")
;                         : "=&v"(sum), "=&v"(y), "=&v"(p1), "=&v"(q1), "=&v"(t0), "=&v"(t1), "=&v"(t2), "=&v"(t3)
;                         : "v"(S0), "v"(S1), "v"(S2), "v"(S3), "v"(a4[0]), "v"(a4[1]), "v"(a4[2]), "v"(a4[3]), "v"(rp[0]), "v"(rp[1]), "v"(rp[2]), "v"(rp[3]),
;                           "v"(vv), "v"(k4[0]), "v"(k4[1]), "v"(k4[2]), "v"(k4[3]));
;                     asm volatile(
;                         "v_fma_f32 %4, -%8, %9, %4\n\t"  "v_fma_f32 %5, -%8, %10, %5\n\t"  "v_fma_f32 %6, -%8, %11, %6\n\t"  "v_fma_f32 %7, -%8, %12, %7\n\t"
	ds_read_b128 v[84:87], v2 offset:13440
	ds_read_b128 v[88:91], v2 offset:15040
	ds_read_b128 v[92:95], v2 offset:15296
	ds_read_b128 v[96:99], v2 offset:15552
	ds_read_b128 v[100:103], v2 offset:15808
	v_pk_mul_f32 v[108:109], v[0:1], v[48:49]
	v_pk_mul_f32 v[110:111], v[0:1], v[36:37]
	v_pk_fma_f32 v[108:109], v[14:15], v[50:51], v[108:109]
	v_pk_fma_f32 v[110:111], v[14:15], v[38:39], v[110:111]
	v_add_f32_e32 v116, v108, v109
	v_add_f32_e32 v137, v110, v111
	v_pk_mul_f32 v[112:113], v[128:129], v[44:45] op_sel:[1,0] op_sel_hi:[1,1]
	v_add_f32_dpp v116, v116, v116 quad_perm:[1,0,3,2] row_mask:0xf bank_mask:0xf bound_ctrl:1
	v_add_f32_dpp v137, v137, v137 quad_perm:[1,0,3,2] row_mask:0xf bank_mask:0xf bound_ctrl:1
	v_pk_mul_f32 v[114:115], v[128:129], v[46:47] op_sel:[1,0] op_sel_hi:[1,1]
	v_add_f32_dpp v116, v116, v116 quad_perm:[2,3,0,1] row_mask:0xf bank_mask:0xf bound_ctrl:1
	v_add_f32_dpp v137, v137, v137 quad_perm:[2,3,0,1] row_mask:0xf bank_mask:0xf bound_ctrl:1
	v_cndmask_b32_e64 v118, v118, v117, s[26:27]
	v_add_f32_dpp v116, v116, v116 row_half_mirror row_mask:0xf bank_mask:0xf bound_ctrl:1
	v_add_f32_dpp v137, v137, v137 row_half_mirror row_mask:0xf bank_mask:0xf bound_ctrl:1
	s_nop 0
	v_add_f32_dpp v116, v116, v116 row_mirror row_mask:0xf bank_mask:0xf bound_ctrl:1
	v_add_f32_dpp v137, v137, v137 row_mirror row_mask:0xf bank_mask:0xf bound_ctrl:1
	v_pk_fma_f32 v[112:113], v[116:117], v[52:53], v[112:113] op_sel_hi:[0,1,1] neg_lo:[1,0,0] neg_hi:[1,0,0]
	v_pk_fma_f32 v[114:115], v[116:117], v[54:55], v[114:115] op_sel_hi:[0,1,1] neg_lo:[1,0,0] neg_hi:[1,0,0]
	v_pk_fma_f32 v[0:1], v[0:1], v[40:41], v[112:113]
	v_pk_fma_f32 v[14:15], v[14:15], v[42:43], v[114:115]
	s_waitcnt lgkmcnt(5)
	ds_read_b128 v[36:39], v2 offset:14784
	ds_read_b128 v[40:43], v2 offset:16384
	ds_read_b128 v[44:47], v2 offset:16640
	ds_read_b128 v[48:51], v2 offset:16896
	ds_read_b128 v[52:55], v2 offset:17152
	ds_read_b128 v[132:135], v126 offset:48
	v_pk_mul_f32 v[108:109], v[0:1], v[72:73]
	v_pk_mul_f32 v[110:111], v[0:1], v[60:61]
	v_pk_fma_f32 v[108:109], v[14:15], v[74:75], v[108:109]
	v_pk_fma_f32 v[110:111], v[14:15], v[62:63], v[110:111]
	v_add_f32_e32 v116, v108, v109
	v_add_f32_e32 v117, v110, v111
	v_pk_mul_f32 v[112:113], v[130:131], v[68:69] op_sel_hi:[0,1]
	v_add_f32_dpp v116, v116, v116 quad_perm:[1,0,3,2] row_mask:0xf bank_mask:0xf bound_ctrl:1
	v_add_f32_dpp v117, v117, v117 quad_perm:[1,0,3,2] row_mask:0xf bank_mask:0xf bound_ctrl:1
	v_pk_mul_f32 v[114:115], v[130:131], v[70:71] op_sel_hi:[0,1]
	v_add_f32_dpp v116, v116, v116 quad_perm:[2,3,0,1] row_mask:0xf bank_mask:0xf bound_ctrl:1
	v_add_f32_dpp v117, v117, v117 quad_perm:[2,3,0,1] row_mask:0xf bank_mask:0xf bound_ctrl:1
	v_cndmask_b32_e64 v118, v118, v137, s[28:29]
	v_add_f32_dpp v116, v116, v116 row_half_mirror row_mask:0xf bank_mask:0xf bound_ctrl:1
	v_add_f32_dpp v117, v117, v117 row_half_mirror row_mask:0xf bank_mask:0xf bound_ctrl:1
	s_nop 0
	v_add_f32_dpp v116, v116, v116 row_mirror row_mask:0xf bank_mask:0xf bound_ctrl:1
	v_add_f32_dpp v117, v117, v117 row_mirror row_mask:0xf bank_mask:0xf bound_ctrl:1
	v_pk_fma_f32 v[112:113], v[116:117], v[76:77], v[112:113] op_sel_hi:[0,1,1] neg_lo:[1,0,0] neg_hi:[1,0,0]
	v_pk_fma_f32 v[114:115], v[116:117], v[78:79], v[114:115] op_sel_hi:[0,1,1] neg_lo:[1,0,0] neg_hi:[1,0,0]
	v_pk_fma_f32 v[0:1], v[0:1], v[64:65], v[112:113]
	v_pk_fma_f32 v[14:15], v[14:15], v[66:67], v[114:115]
	s_waitcnt lgkmcnt(6)
	ds_read_b128 v[60:63], v2 offset:16128
	ds_read_b128 v[64:67], v2 offset:17728
	ds_read_b128 v[68:71], v2 offset:17984
	ds_read_b128 v[72:75], v2 offset:18240
	ds_read_b128 v[76:79], v2 offset:18496
	v_pk_mul_f32 v[108:109], v[0:1], v[96:97]
	v_pk_mul_f32 v[110:111], v[0:1], v[84:85]
	v_pk_fma_f32 v[108:109], v[14:15], v[98:99], v[108:109]
	v_pk_fma_f32 v[110:111], v[14:15], v[86:87], v[110:111]
	v_add_f32_e32 v116, v108, v109
	v_add_f32_e32 v137, v110, v111
	v_pk_mul_f32 v[112:113], v[130:131], v[92:93] op_sel:[1,0] op_sel_hi:[1,1]
	v_add_f32_dpp v116, v116, v116 quad_perm:[1,0,3,2] row_mask:0xf bank_mask:0xf bound_ctrl:1
	v_add_f32_dpp v137, v137, v137 quad_perm:[1,0,3,2] row_mask:0xf bank_mask:0xf bound_ctrl:1
	v_pk_mul_f32 v[114:115], v[130:131], v[94:95] op_sel:[1,0] op_sel_hi:[1,1]
	v_add_f32_dpp v116, v116, v116 quad_perm:[2,3,0,1] row_mask:0xf bank_mask:0xf bound_ctrl:1
	v_add_f32_dpp v137, v137, v137 quad_perm:[2,3,0,1] row_mask:0xf bank_mask:0xf bound_ctrl:1
	v_cndmask_b32_e64 v118, v118, v117, s[30:31]
	v_add_f32_dpp v116, v116, v116 row_half_mirror row_mask:0xf bank_mask:0xf bound_ctrl:1
	v_add_f32_dpp v137, v137, v137 row_half_mirror row_mask:0xf bank_mask:0xf bound_ctrl:1
	s_nop 0
	v_add_f32_dpp v116, v116, v116 row_mirror row_mask:0xf bank_mask:0xf bound_ctrl:1
	v_add_f32_dpp v137, v137, v137 row_mirror row_mask:0xf bank_mask:0xf bound_ctrl:1
	v_pk_fma_f32 v[112:113], v[116:117], v[100:101], v[112:113] op_sel_hi:[0,1,1] neg_lo:[1,0,0] neg_hi:[1,0,0]
	v_pk_fma_f32 v[114:115], v[116:117], v[102:103], v[114:115] op_sel_hi:[0,1,1] neg_lo:[1,0,0] neg_hi:[1,0,0]
	v_pk_fma_f32 v[0:1], v[0:1], v[88:89], v[112:113]
	v_pk_fma_f32 v[14:15], v[14:15], v[90:91], v[114:115]
	s_waitcnt lgkmcnt(5)
; __device__ __forceinline__ void scan_wkv_prompt(PP P, int l, LAS unsigned char* lds, const Ids I) {
;     ...
;                 for (int s = 0; s < 32; ++s) {
;                     f32x4 mr4 = r4, mw4 = w4, mk4 = k4, ma4 = a4, mb4 = b4; float mvv = vv;
;                     if (s < 30) { WKV_LDS6(mr4, mw4, mk4, ma4, mb4, mvv, "s_waitcnt lgkmcnt(6)\n\t", (s + 2) * 1344); }
;                     else if (s == 30) asm volatile("s_waitcnt lgkmcnt(6)" ::: "memory");
;                     else asm volatile("s_waitcnt lgkmcnt(0)" ::: "memory");
;                     __builtin_amdgcn_sched_barrier(0);
;                     float sum, y, p1, q1, t0, t1, t2, t3;
;                     asm volatile(
;                         "v_mul_f32 %0, %8, %12\n\t"  "v_mul_f32 %1, %8, %16\n\t"
;                         "v_fma_f32 %0, %9, %13, %0\n\t"  "v_fma_f32 %1, %9, %17, %1\n\t"
;                         "v_mul_f32 %2, %10, %14\n\t"  "v_mul_f32 %3, %10, %18\n\t"
;                         "v_fma_f32 %2, %11, %15, %2\n\t"  "v_fma_f32 %3, %11, %19, %3\n\t"
;                         "v_add_f32 %0, %0, %2\n\t"  "v_add_f32 %1, %1, %3\n\t"
;                         "v_mul_f32 %4, %20, %21\n\t"  "v_mul_f32 %5, %20, %22\n\t"
;                         DPPA("%0", "quad_perm:[1,0,3,2]") DPPA("%1", "quad_perm:[1,0,3,2]")
;                         "v_mul_f32 %6, %20, %23\n\t"
;                         DPPA("%0", "quad_perm:[2,3,0,1]") DPPA("%1", "quad_perm:[2,3,0,1]")
;                         "v_mul_f32 %7, %20, %24\n\t"
;                         DPPA("%0", "row_half_mirror") DPPA("%1", "row_half_mirror")
;                         "s_nop 0\n\t"
;                         DPPA("%0", "row_mirror") DPPA("%1", "row_mirror")
;                         : "=&v"(sum), "=&v"(y), "=&v"(p1), "=&v"(q1), "=&v"(t0), "=&v"(t1), "=&v"(t2), "=&v"(t3)
;                         : "v"(S0), "v"(S1), "v"(S2), "v"(S3), "v"(a4[0]), "v"(a4[1]), "v"(a4[2]), "v"(a4[3]), "v"(rp[0]), "v"(rp[1]), "v"(rp[2]), "v"(rp[3]),
;                           "v"(vv), "v"(k4[0]), "v"(k4[1]), "v"(k4[2]), "v"(k4[3]));
;                     asm volatile(
;                         "v_fma_f32 %4, -%8, %9, %4\n\t"  "v_fma_f32 %5, -%8, %10, %5\n\t"  "v_fma_f32 %6, -%8, %11, %6\n\t"  "v_fma_f32 %7, -%8, %12, %7\n\t"
	ds_read_b128 v[84:87], v2 offset:17472
	ds_read_b128 v[88:91], v2 offset:19072
	ds_read_b128 v[92:95], v2 offset:19328
	ds_read_b128 v[96:99], v2 offset:19584
	ds_read_b128 v[100:103], v2 offset:19840
	v_pk_mul_f32 v[108:109], v[0:1], v[48:49]
	v_pk_mul_f32 v[110:111], v[0:1], v[36:37]
	v_pk_fma_f32 v[108:109], v[14:15], v[50:51], v[108:109]
	v_pk_fma_f32 v[110:111], v[14:15], v[38:39], v[110:111]
	v_add_f32_e32 v116, v108, v109
	v_add_f32_e32 v117, v110, v111
	v_pk_mul_f32 v[112:113], v[132:133], v[44:45] op_sel_hi:[0,1]
	v_add_f32_dpp v116, v116, v116 quad_perm:[1,0,3,2] row_mask:0xf bank_mask:0xf bound_ctrl:1
	v_add_f32_dpp v117, v117, v117 quad_perm:[1,0,3,2] row_mask:0xf bank_mask:0xf bound_ctrl:1
	v_pk_mul_f32 v[114:115], v[132:133], v[46:47] op_sel_hi:[0,1]
	v_add_f32_dpp v116, v116, v116 quad_perm:[2,3,0,1] row_mask:0xf bank_mask:0xf bound_ctrl:1
	v_add_f32_dpp v117, v117, v117 quad_perm:[2,3,0,1] row_mask:0xf bank_mask:0xf bound_ctrl:1
	v_cndmask_b32_e64 v118, v118, v137, s[34:35]
	v_add_f32_dpp v116, v116, v116 row_half_mirror row_mask:0xf bank_mask:0xf bound_ctrl:1
	v_add_f32_dpp v117, v117, v117 row_half_mirror row_mask:0xf bank_mask:0xf bound_ctrl:1
	s_nop 0
	v_add_f32_dpp v116, v116, v116 row_mirror row_mask:0xf bank_mask:0xf bound_ctrl:1
	v_add_f32_dpp v117, v117, v117 row_mirror row_mask:0xf bank_mask:0xf bound_ctrl:1
	v_pk_fma_f32 v[112:113], v[116:117], v[52:53], v[112:113] op_sel_hi:[0,1,1] neg_lo:[1,0,0] neg_hi:[1,0,0]
	v_pk_fma_f32 v[114:115], v[116:117], v[54:55], v[114:115] op_sel_hi:[0,1,1] neg_lo:[1,0,0] neg_hi:[1,0,0]
	v_pk_fma_f32 v[0:1], v[0:1], v[40:41], v[112:113]
	v_pk_fma_f32 v[14:15], v[14:15], v[42:43], v[114:115]
	s_waitcnt lgkmcnt(5)
	ds_read_b128 v[36:39], v2 offset:18816
	ds_read_b128 v[40:43], v2 offset:20416
	ds_read_b128 v[44:47], v2 offset:20672
	ds_read_b128 v[48:51], v2 offset:20928
	ds_read_b128 v[52:55], v2 offset:21184
	v_pk_mul_f32 v[108:109], v[0:1], v[72:73]
	v_pk_mul_f32 v[110:111], v[0:1], v[60:61]
	v_pk_fma_f32 v[108:109], v[14:15], v[74:75], v[108:109]
	v_pk_fma_f32 v[110:111], v[14:15], v[62:63], v[110:111]
	v_add_f32_e32 v116, v108, v109
	v_add_f32_e32 v137, v110, v111
	v_pk_mul_f32 v[112:113], v[132:133], v[68:69] op_sel:[1,0] op_sel_hi:[1,1]
	v_add_f32_dpp v116, v116, v116 quad_perm:[1,0,3,2] row_mask:0xf bank_mask:0xf bound_ctrl:1
	v_add_f32_dpp v137, v137, v137 quad_perm:[1,0,3,2] row_mask:0xf bank_mask:0xf bound_ctrl:1
	v_pk_mul_f32 v[114:115], v[132:133], v[70:71] op_sel:[1,0] op_sel_hi:[1,1]
	v_add_f32_dpp v116, v116, v116 quad_perm:[2,3,0,1] row_mask:0xf bank_mask:0xf bound_ctrl:1
	v_add_f32_dpp v137, v137, v137 quad_perm:[2,3,0,1] row_mask:0xf bank_mask:0xf bound_ctrl:1
	v_cndmask_b32_e64 v118, v118, v117, s[36:37]
	v_add_f32_dpp v116, v116, v116 row_half_mirror row_mask:0xf bank_mask:0xf bound_ctrl:1
	v_add_f32_dpp v137, v137, v137 row_half_mirror row_mask:0xf bank_mask:0xf bound_ctrl:1
	s_nop 0
	v_add_f32_dpp v116, v116, v116 row_mirror row_mask:0xf bank_mask:0xf bound_ctrl:1
	v_add_f32_dpp v137, v137, v137 row_mirror row_mask:0xf bank_mask:0xf bound_ctrl:1
	v_pk_fma_f32 v[112:113], v[116:117], v[76:77], v[112:113] op_sel_hi:[0,1,1] neg_lo:[1,0,0] neg_hi:[1,0,0]
	v_pk_fma_f32 v[114:115], v[116:117], v[78:79], v[114:115] op_sel_hi:[0,1,1] neg_lo:[1,0,0] neg_hi:[1,0,0]
	v_pk_fma_f32 v[0:1], v[0:1], v[64:65], v[112:113]
	v_pk_fma_f32 v[14:15], v[14:15], v[66:67], v[114:115]
	s_waitcnt lgkmcnt(5)
	ds_read_b128 v[60:63], v2 offset:20160
	ds_read_b128 v[64:67], v2 offset:21760
	ds_read_b128 v[68:71], v2 offset:22016
	ds_read_b128 v[72:75], v2 offset:22272
	ds_read_b128 v[76:79], v2 offset:22528
	ds_read_b128 v[128:131], v126 offset:64
	v_pk_mul_f32 v[108:109], v[0:1], v[96:97]
	v_pk_mul_f32 v[110:111], v[0:1], v[84:85]
	v_pk_fma_f32 v[108:109], v[14:15], v[98:99], v[108:109]
	v_pk_fma_f32 v[110:111], v[14:15], v[86:87], v[110:111]
	v_add_f32_e32 v116, v108, v109
	v_add_f32_e32 v117, v110, v111
	v_pk_mul_f32 v[112:113], v[134:135], v[92:93] op_sel_hi:[0,1]
	v_add_f32_dpp v116, v116, v116 quad_perm:[1,0,3,2] row_mask:0xf bank_mask:0xf bound_ctrl:1
	v_add_f32_dpp v117, v117, v117 quad_perm:[1,0,3,2] row_mask:0xf bank_mask:0xf bound_ctrl:1
	v_pk_mul_f32 v[114:115], v[134:135], v[94:95] op_sel_hi:[0,1]
	v_add_f32_dpp v116, v116, v116 quad_perm:[2,3,0,1] row_mask:0xf bank_mask:0xf bound_ctrl:1
	v_add_f32_dpp v117, v117, v117 quad_perm:[2,3,0,1] row_mask:0xf bank_mask:0xf bound_ctrl:1
	v_cndmask_b32_e64 v118, v118, v137, s[38:39]
	v_add_f32_dpp v116, v116, v116 row_half_mirror row_mask:0xf bank_mask:0xf bound_ctrl:1
	v_add_f32_dpp v117, v117, v117 row_half_mirror row_mask:0xf bank_mask:0xf bound_ctrl:1
	s_nop 0
	v_add_f32_dpp v116, v116, v116 row_mirror row_mask:0xf bank_mask:0xf bound_ctrl:1
	v_add_f32_dpp v117, v117, v117 row_mirror row_mask:0xf bank_mask:0xf bound_ctrl:1
	v_pk_fma_f32 v[112:113], v[116:117], v[100:101], v[112:113] op_sel_hi:[0,1,1] neg_lo:[1,0,0] neg_hi:[1,0,0]
	v_pk_fma_f32 v[114:115], v[116:117], v[102:103], v[114:115] op_sel_hi:[0,1,1] neg_lo:[1,0,0] neg_hi:[1,0,0]
	v_pk_fma_f32 v[0:1], v[0:1], v[88:89], v[112:113]
	v_pk_fma_f32 v[14:15], v[14:15], v[90:91], v[114:115]
	s_waitcnt lgkmcnt(6)
; __device__ __forceinline__ void scan_wkv_prompt(PP P, int l, LAS unsigned char* lds, const Ids I) {
;     ...
;                 for (int s = 0; s < 32; ++s) {
;                     f32x4 mr4 = r4, mw4 = w4, mk4 = k4, ma4 = a4, mb4 = b4; float mvv = vv;
;                     if (s < 30) { WKV_LDS6(mr4, mw4, mk4, ma4, mb4, mvv, "s_waitcnt lgkmcnt(6)\n\t", (s + 2) * 1344); }
;                     else if (s == 30) asm volatile("s_waitcnt lgkmcnt(6)" ::: "memory");
;                     else asm volatile("s_waitcnt lgkmcnt(0)" ::: "memory");
;                     __builtin_amdgcn_sched_barrier(0);
;                     float sum, y, p1, q1, t0, t1, t2, t3;
;                     asm volatile(
;                         "v_mul_f32 %0, %8, %12\n\t"  "v_mul_f32 %1, %8, %16\n\t"
;                         "v_fma_f32 %0, %9, %13, %0\n\t"  "v_fma_f32 %1, %9, %17, %1\n\t"
;                         "v_mul_f32 %2, %10, %14\n\t"  "v_mul_f32 %3, %10, %18\n\t"
;                         "v_fma_f32 %2, %11, %15, %2\n\t"  "v_fma_f32 %3, %11, %19, %3\n\t"
;                         "v_add_f32 %0, %0, %2\n\t"  "v_add_f32 %1, %1, %3\n\t"
;                         "v_mul_f32 %4, %20, %21\n\t"  "v_mul_f32 %5, %20, %22\n\t"
;                         DPPA("%0", "quad_perm:[1,0,3,2]") DPPA("%1", "quad_perm:[1,0,3,2]")
;                         "v_mul_f32 %6, %20, %23\n\t"
;                         DPPA("%0", "quad_perm:[2,3,0,1]") DPPA("%1", "quad_perm:[2,3,0,1]")
;                         "v_mul_f32 %7, %20, %24\n\t"
;                         DPPA("%0", "row_half_mirror") DPPA("%1", "row_half_mirror")
;                         "s_nop 0\n\t"
;                         DPPA("%0", "row_mirror") DPPA("%1", "row_mirror")
;                         : "=&v"(sum), "=&v"(y), "=&v"(p1), "=&v"(q1), "=&v"(t0), "=&v"(t1), "=&v"(t2), "=&v"(t3)
;                         : "v"(S0), "v"(S1), "v"(S2), "v"(S3), "v"(a4[0]), "v"(a4[1]), "v"(a4[2]), "v"(a4[3]), "v"(rp[0]), "v"(rp[1]), "v"(rp[2]), "v"(rp[3]),
;                           "v"(vv), "v"(k4[0]), "v"(k4[1]), "v"(k4[2]), "v"(k4[3]));
;                     asm volatile(
;                         "v_fma_f32 %4, -%8, %9, %4\n\t"  "v_fma_f32 %5, -%8, %10, %5\n\t"  "v_fma_f32 %6, -%8, %11, %6\n\t"  "v_fma_f32 %7, -%8, %12, %7\n\t"
	ds_read_b128 v[84:87], v2 offset:21504
	ds_read_b128 v[88:91], v2 offset:23104
	ds_read_b128 v[92:95], v2 offset:23360
	ds_read_b128 v[96:99], v2 offset:23616
	ds_read_b128 v[100:103], v2 offset:23872
	v_pk_mul_f32 v[108:109], v[0:1], v[48:49]
	v_pk_mul_f32 v[110:111], v[0:1], v[36:37]
	v_pk_fma_f32 v[108:109], v[14:15], v[50:51], v[108:109]
	v_pk_fma_f32 v[110:111], v[14:15], v[38:39], v[110:111]
	v_add_f32_e32 v116, v108, v109
	v_add_f32_e32 v137, v110, v111
	v_pk_mul_f32 v[112:113], v[134:135], v[44:45] op_sel:[1,0] op_sel_hi:[1,1]
	v_add_f32_dpp v116, v116, v116 quad_perm:[1,0,3,2] row_mask:0xf bank_mask:0xf bound_ctrl:1
	v_add_f32_dpp v137, v137, v137 quad_perm:[1,0,3,2] row_mask:0xf bank_mask:0xf bound_ctrl:1
	v_pk_mul_f32 v[114:115], v[134:135], v[46:47] op_sel:[1,0] op_sel_hi:[1,1]
	v_add_f32_dpp v116, v116, v116 quad_perm:[2,3,0,1] row_mask:0xf bank_mask:0xf bound_ctrl:1
	v_add_f32_dpp v137, v137, v137 quad_perm:[2,3,0,1] row_mask:0xf bank_mask:0xf bound_ctrl:1
	v_cndmask_b32_e64 v118, v118, v117, s[40:41]
	v_add_f32_dpp v116, v116, v116 row_half_mirror row_mask:0xf bank_mask:0xf bound_ctrl:1
	v_add_f32_dpp v137, v137, v137 row_half_mirror row_mask:0xf bank_mask:0xf bound_ctrl:1
	s_nop 0
	v_add_f32_dpp v116, v116, v116 row_mirror row_mask:0xf bank_mask:0xf bound_ctrl:1
	v_add_f32_dpp v137, v137, v137 row_mirror row_mask:0xf bank_mask:0xf bound_ctrl:1
	v_pk_fma_f32 v[112:113], v[116:117], v[52:53], v[112:113] op_sel_hi:[0,1,1] neg_lo:[1,0,0] neg_hi:[1,0,0]
	v_pk_fma_f32 v[114:115], v[116:117], v[54:55], v[114:115] op_sel_hi:[0,1,1] neg_lo:[1,0,0] neg_hi:[1,0,0]
	v_pk_fma_f32 v[0:1], v[0:1], v[40:41], v[112:113]
	v_pk_fma_f32 v[14:15], v[14:15], v[42:43], v[114:115]
	s_waitcnt lgkmcnt(5)
	ds_read_b128 v[36:39], v2 offset:22848
	ds_read_b128 v[40:43], v2 offset:24448
	ds_read_b128 v[44:47], v2 offset:24704
	ds_read_b128 v[48:51], v2 offset:24960
	ds_read_b128 v[52:55], v2 offset:25216
	v_pk_mul_f32 v[108:109], v[0:1], v[72:73]
	v_pk_mul_f32 v[110:111], v[0:1], v[60:61]
	v_pk_fma_f32 v[108:109], v[14:15], v[74:75], v[108:109]
	v_pk_fma_f32 v[110:111], v[14:15], v[62:63], v[110:111]
	v_add_f32_e32 v116, v108, v109
	v_add_f32_e32 v117, v110, v111
	v_pk_mul_f32 v[112:113], v[128:129], v[68:69] op_sel_hi:[0,1]
	v_add_f32_dpp v116, v116, v116 quad_perm:[1,0,3,2] row_mask:0xf bank_mask:0xf bound_ctrl:1
	v_add_f32_dpp v117, v117, v117 quad_perm:[1,0,3,2] row_mask:0xf bank_mask:0xf bound_ctrl:1
	v_pk_mul_f32 v[114:115], v[128:129], v[70:71] op_sel_hi:[0,1]
	v_add_f32_dpp v116, v116, v116 quad_perm:[2,3,0,1] row_mask:0xf bank_mask:0xf bound_ctrl:1
	v_add_f32_dpp v117, v117, v117 quad_perm:[2,3,0,1] row_mask:0xf bank_mask:0xf bound_ctrl:1
	v_cndmask_b32_e64 v118, v118, v137, s[42:43]
	v_add_f32_dpp v116, v116, v116 row_half_mirror row_mask:0xf bank_mask:0xf bound_ctrl:1
	v_add_f32_dpp v117, v117, v117 row_half_mirror row_mask:0xf bank_mask:0xf bound_ctrl:1
	v_lshl_add_u32 v119, s45, 11, v33
	v_add_f32_dpp v116, v116, v116 row_mirror row_mask:0xf bank_mask:0xf bound_ctrl:1
	v_add_f32_dpp v117, v117, v117 row_mirror row_mask:0xf bank_mask:0xf bound_ctrl:1
	v_pk_fma_f32 v[112:113], v[116:117], v[76:77], v[112:113] op_sel_hi:[0,1,1] neg_lo:[1,0,0] neg_hi:[1,0,0]
	v_pk_fma_f32 v[114:115], v[116:117], v[78:79], v[114:115] op_sel_hi:[0,1,1] neg_lo:[1,0,0] neg_hi:[1,0,0]
	v_pk_fma_f32 v[0:1], v[0:1], v[64:65], v[112:113]
	v_pk_fma_f32 v[14:15], v[14:15], v[66:67], v[114:115]
	ds_write_b32 v119, v118
	s_waitcnt lgkmcnt(6)
	ds_read_b128 v[60:63], v2 offset:24192
	ds_read_b128 v[64:67], v2 offset:25792
	ds_read_b128 v[68:71], v2 offset:26048
	ds_read_b128 v[72:75], v2 offset:26304
	ds_read_b128 v[76:79], v2 offset:26560
	v_pk_mul_f32 v[108:109], v[0:1], v[96:97]
	v_pk_mul_f32 v[110:111], v[0:1], v[84:85]
	v_pk_fma_f32 v[108:109], v[14:15], v[98:99], v[108:109]
	v_pk_fma_f32 v[110:111], v[14:15], v[86:87], v[110:111]
	v_add_f32_e32 v116, v108, v109
	v_add_f32_e32 v137, v110, v111
	v_pk_mul_f32 v[112:113], v[128:129], v[92:93] op_sel:[1,0] op_sel_hi:[1,1]
	v_add_f32_dpp v116, v116, v116 quad_perm:[1,0,3,2] row_mask:0xf bank_mask:0xf bound_ctrl:1
	v_add_f32_dpp v137, v137, v137 quad_perm:[1,0,3,2] row_mask:0xf bank_mask:0xf bound_ctrl:1
	v_pk_mul_f32 v[114:115], v[128:129], v[94:95] op_sel:[1,0] op_sel_hi:[1,1]
	v_add_f32_dpp v116, v116, v116 quad_perm:[2,3,0,1] row_mask:0xf bank_mask:0xf bound_ctrl:1
	v_add_f32_dpp v137, v137, v137 quad_perm:[2,3,0,1] row_mask:0xf bank_mask:0xf bound_ctrl:1
	v_cndmask_b32_e64 v118, v118, v117, s[4:5]
	v_add_f32_dpp v116, v116, v116 row_half_mirror row_mask:0xf bank_mask:0xf bound_ctrl:1
	v_add_f32_dpp v137, v137, v137 row_half_mirror row_mask:0xf bank_mask:0xf bound_ctrl:1
	s_nop 0
	v_add_f32_dpp v116, v116, v116 row_mirror row_mask:0xf bank_mask:0xf bound_ctrl:1
	v_add_f32_dpp v137, v137, v137 row_mirror row_mask:0xf bank_mask:0xf bound_ctrl:1
	v_pk_fma_f32 v[112:113], v[116:117], v[100:101], v[112:113] op_sel_hi:[0,1,1] neg_lo:[1,0,0] neg_hi:[1,0,0]
	v_pk_fma_f32 v[114:115], v[116:117], v[102:103], v[114:115] op_sel_hi:[0,1,1] neg_lo:[1,0,0] neg_hi:[1,0,0]
	v_pk_fma_f32 v[0:1], v[0:1], v[88:89], v[112:113]
	v_pk_fma_f32 v[14:15], v[14:15], v[90:91], v[114:115]
	s_waitcnt lgkmcnt(6)
; __device__ __forceinline__ void scan_wkv_prompt(PP P, int l, LAS unsigned char* lds, const Ids I) {
;     ...
;                 for (int s = 0; s < 32; ++s) {
;                     f32x4 mr4 = r4, mw4 = w4, mk4 = k4, ma4 = a4, mb4 = b4; float mvv = vv;
;                     if (s < 30) { WKV_LDS6(mr4, mw4, mk4, ma4, mb4, mvv, "s_waitcnt lgkmcnt(6)\n\t", (s + 2) * 1344); }
;                     else if (s == 30) asm volatile("s_waitcnt lgkmcnt(6)" ::: "memory");
;                     else asm volatile("s_waitcnt lgkmcnt(0)" ::: "memory");
;                     __builtin_amdgcn_sched_barrier(0);
;                     float sum, y, p1, q1, t0, t1, t2, t3;
;                     asm volatile(
;                         "v_mul_f32 %0, %8, %12\n\t"  "v_mul_f32 %1, %8, %16\n\t"
;                         "v_fma_f32 %0, %9, %13, %0\n\t"  "v_fma_f32 %1, %9, %17, %1\n\t"
;                         "v_mul_f32 %2, %10, %14\n\t"  "v_mul_f32 %3, %10, %18\n\t"
;                         "v_fma_f32 %2, %11, %15, %2\n\t"  "v_fma_f32 %3, %11, %19, %3\n\t"
;                         "v_add_f32 %0, %0, %2\n\t"  "v_add_f32 %1, %1, %3\n\t"
;                         "v_mul_f32 %4, %20, %21\n\t"  "v_mul_f32 %5, %20, %22\n\t"
;                         DPPA("%0", "quad_perm:[1,0,3,2]") DPPA("%1", "quad_perm:[1,0,3,2]")
;                         "v_mul_f32 %6, %20, %23\n\t"
;                         DPPA("%0", "quad_perm:[2,3,0,1]") DPPA("%1", "quad_perm:[2,3,0,1]")
;                         "v_mul_f32 %7, %20, %24\n\t"
;                         DPPA("%0", "row_half_mirror") DPPA("%1", "row_half_mirror")
;                         "s_nop 0\n\t"
;                         DPPA("%0", "row_mirror") DPPA("%1", "row_mirror")
;                         : "=&v"(sum), "=&v"(y), "=&v"(p1), "=&v"(q1), "=&v"(t0), "=&v"(t1), "=&v"(t2), "=&v"(t3)
;                         : "v"(S0), "v"(S1), "v"(S2), "v"(S3), "v"(a4[0]), "v"(a4[1]), "v"(a4[2]), "v"(a4[3]), "v"(rp[0]), "v"(rp[1]), "v"(rp[2]), "v"(rp[3]),
;                           "v"(vv), "v"(k4[0]), "v"(k4[1]), "v"(k4[2]), "v"(k4[3]));
;                     asm volatile(
;                         "v_fma_f32 %4, -%8, %9, %4\n\t"  "v_fma_f32 %5, -%8, %10, %5\n\t"  "v_fma_f32 %6, -%8, %11, %6\n\t"  "v_fma_f32 %7, -%8, %12, %7\n\t"
	ds_read_b128 v[84:87], v2 offset:25536
	ds_read_b128 v[88:91], v2 offset:27136
	ds_read_b128 v[92:95], v2 offset:27392
	ds_read_b128 v[96:99], v2 offset:27648
	ds_read_b128 v[100:103], v2 offset:27904
	ds_read_b128 v[132:135], v126 offset:80
	v_pk_mul_f32 v[108:109], v[0:1], v[48:49]
	v_pk_mul_f32 v[110:111], v[0:1], v[36:37]
	v_pk_fma_f32 v[108:109], v[14:15], v[50:51], v[108:109]
	v_pk_fma_f32 v[110:111], v[14:15], v[38:39], v[110:111]
	v_add_f32_e32 v116, v108, v109
	v_add_f32_e32 v117, v110, v111
	v_pk_mul_f32 v[112:113], v[130:131], v[44:45] op_sel_hi:[0,1]
	v_add_f32_dpp v116, v116, v116 quad_perm:[1,0,3,2] row_mask:0xf bank_mask:0xf bound_ctrl:1
	v_add_f32_dpp v117, v117, v117 quad_perm:[1,0,3,2] row_mask:0xf bank_mask:0xf bound_ctrl:1
	v_pk_mul_f32 v[114:115], v[130:131], v[46:47] op_sel_hi:[0,1]
	v_add_f32_dpp v116, v116, v116 quad_perm:[2,3,0,1] row_mask:0xf bank_mask:0xf bound_ctrl:1
	v_add_f32_dpp v117, v117, v117 quad_perm:[2,3,0,1] row_mask:0xf bank_mask:0xf bound_ctrl:1
	v_cndmask_b32_e64 v118, v118, v137, s[12:13]
	v_add_f32_dpp v116, v116, v116 row_half_mirror row_mask:0xf bank_mask:0xf bound_ctrl:1
	v_add_f32_dpp v117, v117, v117 row_half_mirror row_mask:0xf bank_mask:0xf bound_ctrl:1
	s_nop 0
	v_add_f32_dpp v116, v116, v116 row_mirror row_mask:0xf bank_mask:0xf bound_ctrl:1
	v_add_f32_dpp v117, v117, v117 row_mirror row_mask:0xf bank_mask:0xf bound_ctrl:1
	v_pk_fma_f32 v[112:113], v[116:117], v[52:53], v[112:113] op_sel_hi:[0,1,1] neg_lo:[1,0,0] neg_hi:[1,0,0]
	v_pk_fma_f32 v[114:115], v[116:117], v[54:55], v[114:115] op_sel_hi:[0,1,1] neg_lo:[1,0,0] neg_hi:[1,0,0]
	v_pk_fma_f32 v[0:1], v[0:1], v[40:41], v[112:113]
	v_pk_fma_f32 v[14:15], v[14:15], v[42:43], v[114:115]
	s_waitcnt lgkmcnt(6)
	ds_read_b128 v[36:39], v2 offset:26880
	ds_read_b128 v[40:43], v2 offset:28480
	ds_read_b128 v[44:47], v2 offset:28736
	ds_read_b128 v[48:51], v2 offset:28992
	ds_read_b128 v[52:55], v2 offset:29248
	v_pk_mul_f32 v[108:109], v[0:1], v[72:73]
	v_pk_mul_f32 v[110:111], v[0:1], v[60:61]
	v_pk_fma_f32 v[108:109], v[14:15], v[74:75], v[108:109]
	v_pk_fma_f32 v[110:111], v[14:15], v[62:63], v[110:111]
	v_add_f32_e32 v116, v108, v109
	v_add_f32_e32 v137, v110, v111
	v_pk_mul_f32 v[112:113], v[130:131], v[68:69] op_sel:[1,0] op_sel_hi:[1,1]
	v_add_f32_dpp v116, v116, v116 quad_perm:[1,0,3,2] row_mask:0xf bank_mask:0xf bound_ctrl:1
	v_add_f32_dpp v137, v137, v137 quad_perm:[1,0,3,2] row_mask:0xf bank_mask:0xf bound_ctrl:1
	v_pk_mul_f32 v[114:115], v[130:131], v[70:71] op_sel:[1,0] op_sel_hi:[1,1]
	v_add_f32_dpp v116, v116, v116 quad_perm:[2,3,0,1] row_mask:0xf bank_mask:0xf bound_ctrl:1
	v_add_f32_dpp v137, v137, v137 quad_perm:[2,3,0,1] row_mask:0xf bank_mask:0xf bound_ctrl:1
	v_cndmask_b32_e64 v118, v118, v117, s[14:15]
	v_add_f32_dpp v116, v116, v116 row_half_mirror row_mask:0xf bank_mask:0xf bound_ctrl:1
	v_add_f32_dpp v137, v137, v137 row_half_mirror row_mask:0xf bank_mask:0xf bound_ctrl:1
	s_nop 0
	v_add_f32_dpp v116, v116, v116 row_mirror row_mask:0xf bank_mask:0xf bound_ctrl:1
	v_add_f32_dpp v137, v137, v137 row_mirror row_mask:0xf bank_mask:0xf bound_ctrl:1
	v_pk_fma_f32 v[112:113], v[116:117], v[76:77], v[112:113] op_sel_hi:[0,1,1] neg_lo:[1,0,0] neg_hi:[1,0,0]
	v_pk_fma_f32 v[114:115], v[116:117], v[78:79], v[114:115] op_sel_hi:[0,1,1] neg_lo:[1,0,0] neg_hi:[1,0,0]
	v_pk_fma_f32 v[0:1], v[0:1], v[64:65], v[112:113]
	v_pk_fma_f32 v[14:15], v[14:15], v[66:67], v[114:115]
	s_waitcnt lgkmcnt(5)
	ds_read_b128 v[60:63], v2 offset:28224
	ds_read_b128 v[64:67], v2 offset:29824
	ds_read_b128 v[68:71], v2 offset:30080
	ds_read_b128 v[72:75], v2 offset:30336
	ds_read_b128 v[76:79], v2 offset:30592
	v_pk_mul_f32 v[108:109], v[0:1], v[96:97]
	v_pk_mul_f32 v[110:111], v[0:1], v[84:85]
	v_pk_fma_f32 v[108:109], v[14:15], v[98:99], v[108:109]
	v_pk_fma_f32 v[110:111], v[14:15], v[86:87], v[110:111]
	v_add_f32_e32 v116, v108, v109
	v_add_f32_e32 v117, v110, v111
	v_pk_mul_f32 v[112:113], v[132:133], v[92:93] op_sel_hi:[0,1]
	v_add_f32_dpp v116, v116, v116 quad_perm:[1,0,3,2] row_mask:0xf bank_mask:0xf bound_ctrl:1
	v_add_f32_dpp v117, v117, v117 quad_perm:[1,0,3,2] row_mask:0xf bank_mask:0xf bound_ctrl:1
	v_pk_mul_f32 v[114:115], v[132:133], v[94:95] op_sel_hi:[0,1]
	v_add_f32_dpp v116, v116, v116 quad_perm:[2,3,0,1] row_mask:0xf bank_mask:0xf bound_ctrl:1
	v_add_f32_dpp v117, v117, v117 quad_perm:[2,3,0,1] row_mask:0xf bank_mask:0xf bound_ctrl:1
	v_cndmask_b32_e64 v118, v118, v137, s[16:17]
	v_add_f32_dpp v116, v116, v116 row_half_mirror row_mask:0xf bank_mask:0xf bound_ctrl:1
	v_add_f32_dpp v117, v117, v117 row_half_mirror row_mask:0xf bank_mask:0xf bound_ctrl:1
	s_nop 0
	v_add_f32_dpp v116, v116, v116 row_mirror row_mask:0xf bank_mask:0xf bound_ctrl:1
	v_add_f32_dpp v117, v117, v117 row_mirror row_mask:0xf bank_mask:0xf bound_ctrl:1
	v_pk_fma_f32 v[112:113], v[116:117], v[100:101], v[112:113] op_sel_hi:[0,1,1] neg_lo:[1,0,0] neg_hi:[1,0,0]
	v_pk_fma_f32 v[114:115], v[116:117], v[102:103], v[114:115] op_sel_hi:[0,1,1] neg_lo:[1,0,0] neg_hi:[1,0,0]
	v_pk_fma_f32 v[0:1], v[0:1], v[88:89], v[112:113]
	v_pk_fma_f32 v[14:15], v[14:15], v[90:91], v[114:115]
	s_waitcnt lgkmcnt(5)
; __device__ __forceinline__ void scan_wkv_prompt(PP P, int l, LAS unsigned char* lds, const Ids I) {
;     ...
;                 for (int s = 0; s < 32; ++s) {
;                     f32x4 mr4 = r4, mw4 = w4, mk4 = k4, ma4 = a4, mb4 = b4; float mvv = vv;
;                     if (s < 30) { WKV_LDS6(mr4, mw4, mk4, ma4, mb4, mvv, "s_waitcnt lgkmcnt(6)\n\t", (s + 2) * 1344); }
;                     else if (s == 30) asm volatile("s_waitcnt lgkmcnt(6)" ::: "memory");
;                     else asm volatile("s_waitcnt lgkmcnt(0)" ::: "memory");
;                     __builtin_amdgcn_sched_barrier(0);
;                     float sum, y, p1, q1, t0, t1, t2, t3;
;                     asm volatile(
;                         "v_mul_f32 %0, %8, %12\n\t"  "v_mul_f32 %1, %8, %16\n\t"
;                         "v_fma_f32 %0, %9, %13, %0\n\t"  "v_fma_f32 %1, %9, %17, %1\n\t"
;                         "v_mul_f32 %2, %10, %14\n\t"  "v_mul_f32 %3, %10, %18\n\t"
;                         "v_fma_f32 %2, %11, %15, %2\n\t"  "v_fma_f32 %3, %11, %19, %3\n\t"
;                         "v_add_f32 %0, %0, %2\n\t"  "v_add_f32 %1, %1, %3\n\t"
;                         "v_mul_f32 %4, %20, %21\n\t"  "v_mul_f32 %5, %20, %22\n\t"
;                         DPPA("%0", "quad_perm:[1,0,3,2]") DPPA("%1", "quad_perm:[1,0,3,2]")
;                         "v_mul_f32 %6, %20, %23\n\t"
;                         DPPA("%0", "quad_perm:[2,3,0,1]") DPPA("%1", "quad_perm:[2,3,0,1]")
;                         "v_mul_f32 %7, %20, %24\n\t"
;                         DPPA("%0", "row_half_mirror") DPPA("%1", "row_half_mirror")
;                         "s_nop 0\n\t"
;                         DPPA("%0", "row_mirror") DPPA("%1", "row_mirror")
;                         : "=&v"(sum), "=&v"(y), "=&v"(p1), "=&v"(q1), "=&v"(t0), "=&v"(t1), "=&v"(t2), "=&v"(t3)
;                         : "v"(S0), "v"(S1), "v"(S2), "v"(S3), "v"(a4[0]), "v"(a4[1]), "v"(a4[2]), "v"(a4[3]), "v"(rp[0]), "v"(rp[1]), "v"(rp[2]), "v"(rp[3]),
;                           "v"(vv), "v"(k4[0]), "v"(k4[1]), "v"(k4[2]), "v"(k4[3]));
;                     asm volatile(
;                         "v_fma_f32 %4, -%8, %9, %4\n\t"  "v_fma_f32 %5, -%8, %10, %5\n\t"  "v_fma_f32 %6, -%8, %11, %6\n\t"  "v_fma_f32 %7, -%8, %12, %7\n\t"
	ds_read_b128 v[84:87], v2 offset:29568
	ds_read_b128 v[88:91], v2 offset:31168
	ds_read_b128 v[92:95], v2 offset:31424
	ds_read_b128 v[96:99], v2 offset:31680
	ds_read_b128 v[100:103], v2 offset:31936
	v_pk_mul_f32 v[108:109], v[0:1], v[48:49]
	v_pk_mul_f32 v[110:111], v[0:1], v[36:37]
	v_pk_fma_f32 v[108:109], v[14:15], v[50:51], v[108:109]
	v_pk_fma_f32 v[110:111], v[14:15], v[38:39], v[110:111]
	v_add_f32_e32 v116, v108, v109
	v_add_f32_e32 v137, v110, v111
	v_pk_mul_f32 v[112:113], v[132:133], v[44:45] op_sel:[1,0] op_sel_hi:[1,1]
	v_add_f32_dpp v116, v116, v116 quad_perm:[1,0,3,2] row_mask:0xf bank_mask:0xf bound_ctrl:1
	v_add_f32_dpp v137, v137, v137 quad_perm:[1,0,3,2] row_mask:0xf bank_mask:0xf bound_ctrl:1
	v_pk_mul_f32 v[114:115], v[132:133], v[46:47] op_sel:[1,0] op_sel_hi:[1,1]
	v_add_f32_dpp v116, v116, v116 quad_perm:[2,3,0,1] row_mask:0xf bank_mask:0xf bound_ctrl:1
	v_add_f32_dpp v137, v137, v137 quad_perm:[2,3,0,1] row_mask:0xf bank_mask:0xf bound_ctrl:1
	v_cndmask_b32_e64 v118, v118, v117, s[18:19]
	v_add_f32_dpp v116, v116, v116 row_half_mirror row_mask:0xf bank_mask:0xf bound_ctrl:1
	v_add_f32_dpp v137, v137, v137 row_half_mirror row_mask:0xf bank_mask:0xf bound_ctrl:1
	s_nop 0
	v_add_f32_dpp v116, v116, v116 row_mirror row_mask:0xf bank_mask:0xf bound_ctrl:1
	v_add_f32_dpp v137, v137, v137 row_mirror row_mask:0xf bank_mask:0xf bound_ctrl:1
	v_pk_fma_f32 v[112:113], v[116:117], v[52:53], v[112:113] op_sel_hi:[0,1,1] neg_lo:[1,0,0] neg_hi:[1,0,0]
	v_pk_fma_f32 v[114:115], v[116:117], v[54:55], v[114:115] op_sel_hi:[0,1,1] neg_lo:[1,0,0] neg_hi:[1,0,0]
	v_pk_fma_f32 v[0:1], v[0:1], v[40:41], v[112:113]
	v_pk_fma_f32 v[14:15], v[14:15], v[42:43], v[114:115]
	s_waitcnt lgkmcnt(5)
	ds_read_b128 v[36:39], v2 offset:30912
	ds_read_b128 v[40:43], v2 offset:32512
	ds_read_b128 v[44:47], v2 offset:32768
	ds_read_b128 v[48:51], v2 offset:33024
	ds_read_b128 v[52:55], v2 offset:33280
	ds_read_b128 v[128:131], v126 offset:96
	v_pk_mul_f32 v[108:109], v[0:1], v[72:73]
	v_pk_mul_f32 v[110:111], v[0:1], v[60:61]
	v_pk_fma_f32 v[108:109], v[14:15], v[74:75], v[108:109]
	v_pk_fma_f32 v[110:111], v[14:15], v[62:63], v[110:111]
	v_add_f32_e32 v116, v108, v109
	v_add_f32_e32 v117, v110, v111
	v_pk_mul_f32 v[112:113], v[134:135], v[68:69] op_sel_hi:[0,1]
	v_add_f32_dpp v116, v116, v116 quad_perm:[1,0,3,2] row_mask:0xf bank_mask:0xf bound_ctrl:1
	v_add_f32_dpp v117, v117, v117 quad_perm:[1,0,3,2] row_mask:0xf bank_mask:0xf bound_ctrl:1
	v_pk_mul_f32 v[114:115], v[134:135], v[70:71] op_sel_hi:[0,1]
	v_add_f32_dpp v116, v116, v116 quad_perm:[2,3,0,1] row_mask:0xf bank_mask:0xf bound_ctrl:1
	v_add_f32_dpp v117, v117, v117 quad_perm:[2,3,0,1] row_mask:0xf bank_mask:0xf bound_ctrl:1
	v_cndmask_b32_e64 v118, v118, v137, s[20:21]
	v_add_f32_dpp v116, v116, v116 row_half_mirror row_mask:0xf bank_mask:0xf bound_ctrl:1
	v_add_f32_dpp v117, v117, v117 row_half_mirror row_mask:0xf bank_mask:0xf bound_ctrl:1
	s_nop 0
	v_add_f32_dpp v116, v116, v116 row_mirror row_mask:0xf bank_mask:0xf bound_ctrl:1
	v_add_f32_dpp v117, v117, v117 row_mirror row_mask:0xf bank_mask:0xf bound_ctrl:1
	v_pk_fma_f32 v[112:113], v[116:117], v[76:77], v[112:113] op_sel_hi:[0,1,1] neg_lo:[1,0,0] neg_hi:[1,0,0]
	v_pk_fma_f32 v[114:115], v[116:117], v[78:79], v[114:115] op_sel_hi:[0,1,1] neg_lo:[1,0,0] neg_hi:[1,0,0]
	v_pk_fma_f32 v[0:1], v[0:1], v[64:65], v[112:113]
	v_pk_fma_f32 v[14:15], v[14:15], v[66:67], v[114:115]
	s_waitcnt lgkmcnt(6)
	ds_read_b128 v[60:63], v2 offset:32256
	ds_read_b128 v[64:67], v2 offset:33856
	ds_read_b128 v[68:71], v2 offset:34112
	ds_read_b128 v[72:75], v2 offset:34368
	ds_read_b128 v[76:79], v2 offset:34624
	v_pk_mul_f32 v[108:109], v[0:1], v[96:97]
	v_pk_mul_f32 v[110:111], v[0:1], v[84:85]
	v_pk_fma_f32 v[108:109], v[14:15], v[98:99], v[108:109]
	v_pk_fma_f32 v[110:111], v[14:15], v[86:87], v[110:111]
	v_add_f32_e32 v116, v108, v109
	v_add_f32_e32 v137, v110, v111
	v_pk_mul_f32 v[112:113], v[134:135], v[92:93] op_sel:[1,0] op_sel_hi:[1,1]
	v_add_f32_dpp v116, v116, v116 quad_perm:[1,0,3,2] row_mask:0xf bank_mask:0xf bound_ctrl:1
	v_add_f32_dpp v137, v137, v137 quad_perm:[1,0,3,2] row_mask:0xf bank_mask:0xf bound_ctrl:1
	v_pk_mul_f32 v[114:115], v[134:135], v[94:95] op_sel:[1,0] op_sel_hi:[1,1]
	v_add_f32_dpp v116, v116, v116 quad_perm:[2,3,0,1] row_mask:0xf bank_mask:0xf bound_ctrl:1
	v_add_f32_dpp v137, v137, v137 quad_perm:[2,3,0,1] row_mask:0xf bank_mask:0xf bound_ctrl:1
	v_cndmask_b32_e64 v118, v118, v117, s[22:23]
	v_add_f32_dpp v116, v116, v116 row_half_mirror row_mask:0xf bank_mask:0xf bound_ctrl:1
	v_add_f32_dpp v137, v137, v137 row_half_mirror row_mask:0xf bank_mask:0xf bound_ctrl:1
	s_nop 0
	v_add_f32_dpp v116, v116, v116 row_mirror row_mask:0xf bank_mask:0xf bound_ctrl:1
	v_add_f32_dpp v137, v137, v137 row_mirror row_mask:0xf bank_mask:0xf bound_ctrl:1
	v_pk_fma_f32 v[112:113], v[116:117], v[100:101], v[112:113] op_sel_hi:[0,1,1] neg_lo:[1,0,0] neg_hi:[1,0,0]
	v_pk_fma_f32 v[114:115], v[116:117], v[102:103], v[114:115] op_sel_hi:[0,1,1] neg_lo:[1,0,0] neg_hi:[1,0,0]
	v_pk_fma_f32 v[0:1], v[0:1], v[88:89], v[112:113]
	v_pk_fma_f32 v[14:15], v[14:15], v[90:91], v[114:115]
	s_waitcnt lgkmcnt(5)
; __device__ __forceinline__ void scan_wkv_prompt(PP P, int l, LAS unsigned char* lds, const Ids I) {
;     ...
;                 for (int s = 0; s < 32; ++s) {
;                     f32x4 mr4 = r4, mw4 = w4, mk4 = k4, ma4 = a4, mb4 = b4; float mvv = vv;
;                     if (s < 30) { WKV_LDS6(mr4, mw4, mk4, ma4, mb4, mvv, "s_waitcnt lgkmcnt(6)\n\t", (s + 2) * 1344); }
;                     else if (s == 30) asm volatile("s_waitcnt lgkmcnt(6)" ::: "memory");
;                     else asm volatile("s_waitcnt lgkmcnt(0)" ::: "memory");
;                     __builtin_amdgcn_sched_barrier(0);
;                     float sum, y, p1, q1, t0, t1, t2, t3;
;                     asm volatile(
;                         "v_mul_f32 %0, %8, %12\n\t"  "v_mul_f32 %1, %8, %16\n\t"
;                         "v_fma_f32 %0, %9, %13, %0\n\t"  "v_fma_f32 %1, %9, %17, %1\n\t"
;                         "v_mul_f32 %2, %10, %14\n\t"  "v_mul_f32 %3, %10, %18\n\t"
;                         "v_fma_f32 %2, %11, %15, %2\n\t"  "v_fma_f32 %3, %11, %19, %3\n\t"
;                         "v_add_f32 %0, %0, %2\n\t"  "v_add_f32 %1, %1, %3\n\t"
;                         "v_mul_f32 %4, %20, %21\n\t"  "v_mul_f32 %5, %20, %22\n\t"
;                         DPPA("%0", "quad_perm:[1,0,3,2]") DPPA("%1", "quad_perm:[1,0,3,2]")
;                         "v_mul_f32 %6, %20, %23\n\t"
;                         DPPA("%0", "quad_perm:[2,3,0,1]") DPPA("%1", "quad_perm:[2,3,0,1]")
;                         "v_mul_f32 %7, %20, %24\n\t"
;                         DPPA("%0", "row_half_mirror") DPPA("%1", "row_half_mirror")
;                         "s_nop 0\n\t"
;                         DPPA("%0", "row_mirror") DPPA("%1", "row_mirror")
;                         : "=&v"(sum), "=&v"(y), "=&v"(p1), "=&v"(q1), "=&v"(t0), "=&v"(t1), "=&v"(t2), "=&v"(t3)
;                         : "v"(S0), "v"(S1), "v"(S2), "v"(S3), "v"(a4[0]), "v"(a4[1]), "v"(a4[2]), "v"(a4[3]), "v"(rp[0]), "v"(rp[1]), "v"(rp[2]), "v"(rp[3]),
;                           "v"(vv), "v"(k4[0]), "v"(k4[1]), "v"(k4[2]), "v"(k4[3]));
;                     asm volatile(
;                         "v_fma_f32 %4, -%8, %9, %4\n\t"  "v_fma_f32 %5, -%8, %10, %5\n\t"  "v_fma_f32 %6, -%8, %11, %6\n\t"  "v_fma_f32 %7, -%8, %12, %7\n\t"
	ds_read_b128 v[84:87], v2 offset:33600
	ds_read_b128 v[88:91], v2 offset:35200
	ds_read_b128 v[92:95], v2 offset:35456
	ds_read_b128 v[96:99], v2 offset:35712
	ds_read_b128 v[100:103], v2 offset:35968
	v_pk_mul_f32 v[108:109], v[0:1], v[48:49]
	v_pk_mul_f32 v[110:111], v[0:1], v[36:37]
	v_pk_fma_f32 v[108:109], v[14:15], v[50:51], v[108:109]
	v_pk_fma_f32 v[110:111], v[14:15], v[38:39], v[110:111]
	v_add_f32_e32 v116, v108, v109
	v_add_f32_e32 v117, v110, v111
	v_pk_mul_f32 v[112:113], v[128:129], v[44:45] op_sel_hi:[0,1]
	v_add_f32_dpp v116, v116, v116 quad_perm:[1,0,3,2] row_mask:0xf bank_mask:0xf bound_ctrl:1
	v_add_f32_dpp v117, v117, v117 quad_perm:[1,0,3,2] row_mask:0xf bank_mask:0xf bound_ctrl:1
	v_pk_mul_f32 v[114:115], v[128:129], v[46:47] op_sel_hi:[0,1]
	v_add_f32_dpp v116, v116, v116 quad_perm:[2,3,0,1] row_mask:0xf bank_mask:0xf bound_ctrl:1
	v_add_f32_dpp v117, v117, v117 quad_perm:[2,3,0,1] row_mask:0xf bank_mask:0xf bound_ctrl:1
	v_cndmask_b32_e64 v118, v118, v137, s[24:25]
	v_add_f32_dpp v116, v116, v116 row_half_mirror row_mask:0xf bank_mask:0xf bound_ctrl:1
	v_add_f32_dpp v117, v117, v117 row_half_mirror row_mask:0xf bank_mask:0xf bound_ctrl:1
	s_nop 0
	v_add_f32_dpp v116, v116, v116 row_mirror row_mask:0xf bank_mask:0xf bound_ctrl:1
	v_add_f32_dpp v117, v117, v117 row_mirror row_mask:0xf bank_mask:0xf bound_ctrl:1
	v_pk_fma_f32 v[112:113], v[116:117], v[52:53], v[112:113] op_sel_hi:[0,1,1] neg_lo:[1,0,0] neg_hi:[1,0,0]
	v_pk_fma_f32 v[114:115], v[116:117], v[54:55], v[114:115] op_sel_hi:[0,1,1] neg_lo:[1,0,0] neg_hi:[1,0,0]
	v_pk_fma_f32 v[0:1], v[0:1], v[40:41], v[112:113]
	v_pk_fma_f32 v[14:15], v[14:15], v[42:43], v[114:115]
	s_waitcnt lgkmcnt(5)
	ds_read_b128 v[36:39], v2 offset:34944
	ds_read_b128 v[40:43], v2 offset:36544
	ds_read_b128 v[44:47], v2 offset:36800
	ds_read_b128 v[48:51], v2 offset:37056
	ds_read_b128 v[52:55], v2 offset:37312
	v_pk_mul_f32 v[108:109], v[0:1], v[72:73]
	v_pk_mul_f32 v[110:111], v[0:1], v[60:61]
	v_pk_fma_f32 v[108:109], v[14:15], v[74:75], v[108:109]
	v_pk_fma_f32 v[110:111], v[14:15], v[62:63], v[110:111]
	v_add_f32_e32 v116, v108, v109
	v_add_f32_e32 v137, v110, v111
	v_pk_mul_f32 v[112:113], v[128:129], v[68:69] op_sel:[1,0] op_sel_hi:[1,1]
	v_add_f32_dpp v116, v116, v116 quad_perm:[1,0,3,2] row_mask:0xf bank_mask:0xf bound_ctrl:1
	v_add_f32_dpp v137, v137, v137 quad_perm:[1,0,3,2] row_mask:0xf bank_mask:0xf bound_ctrl:1
	v_pk_mul_f32 v[114:115], v[128:129], v[70:71] op_sel:[1,0] op_sel_hi:[1,1]
	v_add_f32_dpp v116, v116, v116 quad_perm:[2,3,0,1] row_mask:0xf bank_mask:0xf bound_ctrl:1
	v_add_f32_dpp v137, v137, v137 quad_perm:[2,3,0,1] row_mask:0xf bank_mask:0xf bound_ctrl:1
	v_cndmask_b32_e64 v118, v118, v117, s[26:27]
	v_add_f32_dpp v116, v116, v116 row_half_mirror row_mask:0xf bank_mask:0xf bound_ctrl:1
	v_add_f32_dpp v137, v137, v137 row_half_mirror row_mask:0xf bank_mask:0xf bound_ctrl:1
	s_nop 0
	v_add_f32_dpp v116, v116, v116 row_mirror row_mask:0xf bank_mask:0xf bound_ctrl:1
	v_add_f32_dpp v137, v137, v137 row_mirror row_mask:0xf bank_mask:0xf bound_ctrl:1
	v_pk_fma_f32 v[112:113], v[116:117], v[76:77], v[112:113] op_sel_hi:[0,1,1] neg_lo:[1,0,0] neg_hi:[1,0,0]
	v_pk_fma_f32 v[114:115], v[116:117], v[78:79], v[114:115] op_sel_hi:[0,1,1] neg_lo:[1,0,0] neg_hi:[1,0,0]
	v_pk_fma_f32 v[0:1], v[0:1], v[64:65], v[112:113]
	v_pk_fma_f32 v[14:15], v[14:15], v[66:67], v[114:115]
	s_waitcnt lgkmcnt(5)
	ds_read_b128 v[60:63], v2 offset:36288
	ds_read_b128 v[64:67], v2 offset:37888
	ds_read_b128 v[68:71], v2 offset:38144
	ds_read_b128 v[72:75], v2 offset:38400
	ds_read_b128 v[76:79], v2 offset:38656
	ds_read_b128 v[132:135], v126 offset:112
	v_pk_mul_f32 v[108:109], v[0:1], v[96:97]
	v_pk_mul_f32 v[110:111], v[0:1], v[84:85]
	v_pk_fma_f32 v[108:109], v[14:15], v[98:99], v[108:109]
	v_pk_fma_f32 v[110:111], v[14:15], v[86:87], v[110:111]
	v_add_f32_e32 v116, v108, v109
	v_add_f32_e32 v117, v110, v111
	v_pk_mul_f32 v[112:113], v[130:131], v[92:93] op_sel_hi:[0,1]
	v_add_f32_dpp v116, v116, v116 quad_perm:[1,0,3,2] row_mask:0xf bank_mask:0xf bound_ctrl:1
	v_add_f32_dpp v117, v117, v117 quad_perm:[1,0,3,2] row_mask:0xf bank_mask:0xf bound_ctrl:1
	v_pk_mul_f32 v[114:115], v[130:131], v[94:95] op_sel_hi:[0,1]
	v_add_f32_dpp v116, v116, v116 quad_perm:[2,3,0,1] row_mask:0xf bank_mask:0xf bound_ctrl:1
	v_add_f32_dpp v117, v117, v117 quad_perm:[2,3,0,1] row_mask:0xf bank_mask:0xf bound_ctrl:1
	v_cndmask_b32_e64 v118, v118, v137, s[28:29]
	v_add_f32_dpp v116, v116, v116 row_half_mirror row_mask:0xf bank_mask:0xf bound_ctrl:1
	v_add_f32_dpp v117, v117, v117 row_half_mirror row_mask:0xf bank_mask:0xf bound_ctrl:1
	s_nop 0
	v_add_f32_dpp v116, v116, v116 row_mirror row_mask:0xf bank_mask:0xf bound_ctrl:1
	v_add_f32_dpp v117, v117, v117 row_mirror row_mask:0xf bank_mask:0xf bound_ctrl:1
	v_pk_fma_f32 v[112:113], v[116:117], v[100:101], v[112:113] op_sel_hi:[0,1,1] neg_lo:[1,0,0] neg_hi:[1,0,0]
	v_pk_fma_f32 v[114:115], v[116:117], v[102:103], v[114:115] op_sel_hi:[0,1,1] neg_lo:[1,0,0] neg_hi:[1,0,0]
	v_pk_fma_f32 v[0:1], v[0:1], v[88:89], v[112:113]
	v_pk_fma_f32 v[14:15], v[14:15], v[90:91], v[114:115]
	s_waitcnt lgkmcnt(6)
; __device__ __forceinline__ void scan_wkv_prompt(PP P, int l, LAS unsigned char* lds, const Ids I) {
;     ...
;                 for (int s = 0; s < 32; ++s) {
;                     f32x4 mr4 = r4, mw4 = w4, mk4 = k4, ma4 = a4, mb4 = b4; float mvv = vv;
;                     if (s < 30) { WKV_LDS6(mr4, mw4, mk4, ma4, mb4, mvv, "s_waitcnt lgkmcnt(6)\n\t", (s + 2) * 1344); }
;                     else if (s == 30) asm volatile("s_waitcnt lgkmcnt(6)" ::: "memory");
;                     else asm volatile("s_waitcnt lgkmcnt(0)" ::: "memory");
;                     __builtin_amdgcn_sched_barrier(0);
;                     float sum, y, p1, q1, t0, t1, t2, t3;
;                     asm volatile(
;                         "v_mul_f32 %0, %8, %12\n\t"  "v_mul_f32 %1, %8, %16\n\t"
;                         "v_fma_f32 %0, %9, %13, %0\n\t"  "v_fma_f32 %1, %9, %17, %1\n\t"
;                         "v_mul_f32 %2, %10, %14\n\t"  "v_mul_f32 %3, %10, %18\n\t"
;                         "v_fma_f32 %2, %11, %15, %2\n\t"  "v_fma_f32 %3, %11, %19, %3\n\t"
;                         "v_add_f32 %0, %0, %2\n\t"  "v_add_f32 %1, %1, %3\n\t"
;                         "v_mul_f32 %4, %20, %21\n\t"  "v_mul_f32 %5, %20, %22\n\t"
;                         DPPA("%0", "quad_perm:[1,0,3,2]") DPPA("%1", "quad_perm:[1,0,3,2]")
;                         "v_mul_f32 %6, %20, %23\n\t"
;                         DPPA("%0", "quad_perm:[2,3,0,1]") DPPA("%1", "quad_perm:[2,3,0,1]")
;                         "v_mul_f32 %7, %20, %24\n\t"
;                         DPPA("%0", "row_half_mirror") DPPA("%1", "row_half_mirror")
;                         "s_nop 0\n\t"
;                         DPPA("%0", "row_mirror") DPPA("%1", "row_mirror")
;                         : "=&v"(sum), "=&v"(y), "=&v"(p1), "=&v"(q1), "=&v"(t0), "=&v"(t1), "=&v"(t2), "=&v"(t3)
;                         : "v"(S0), "v"(S1), "v"(S2), "v"(S3), "v"(a4[0]), "v"(a4[1]), "v"(a4[2]), "v"(a4[3]), "v"(rp[0]), "v"(rp[1]), "v"(rp[2]), "v"(rp[3]),
;                           "v"(vv), "v"(k4[0]), "v"(k4[1]), "v"(k4[2]), "v"(k4[3]));
;                     asm volatile(
;                         "v_fma_f32 %4, -%8, %9, %4\n\t"  "v_fma_f32 %5, -%8, %10, %5\n\t"  "v_fma_f32 %6, -%8, %11, %6\n\t"  "v_fma_f32 %7, -%8, %12, %7\n\t"
	ds_read_b128 v[84:87], v2 offset:37632
	ds_read_b128 v[88:91], v2 offset:39232
	ds_read_b128 v[92:95], v2 offset:39488
	ds_read_b128 v[96:99], v2 offset:39744
	ds_read_b128 v[100:103], v2 offset:40000
	v_pk_mul_f32 v[108:109], v[0:1], v[48:49]
	v_pk_mul_f32 v[110:111], v[0:1], v[36:37]
	v_pk_fma_f32 v[108:109], v[14:15], v[50:51], v[108:109]
	v_pk_fma_f32 v[110:111], v[14:15], v[38:39], v[110:111]
	v_add_f32_e32 v116, v108, v109
	v_add_f32_e32 v137, v110, v111
	v_pk_mul_f32 v[112:113], v[130:131], v[44:45] op_sel:[1,0] op_sel_hi:[1,1]
	v_add_f32_dpp v116, v116, v116 quad_perm:[1,0,3,2] row_mask:0xf bank_mask:0xf bound_ctrl:1
	v_add_f32_dpp v137, v137, v137 quad_perm:[1,0,3,2] row_mask:0xf bank_mask:0xf bound_ctrl:1
	v_pk_mul_f32 v[114:115], v[130:131], v[46:47] op_sel:[1,0] op_sel_hi:[1,1]
	v_add_f32_dpp v116, v116, v116 quad_perm:[2,3,0,1] row_mask:0xf bank_mask:0xf bound_ctrl:1
	v_add_f32_dpp v137, v137, v137 quad_perm:[2,3,0,1] row_mask:0xf bank_mask:0xf bound_ctrl:1
	v_cndmask_b32_e64 v118, v118, v117, s[30:31]
	v_add_f32_dpp v116, v116, v116 row_half_mirror row_mask:0xf bank_mask:0xf bound_ctrl:1
	v_add_f32_dpp v137, v137, v137 row_half_mirror row_mask:0xf bank_mask:0xf bound_ctrl:1
	s_nop 0
	v_add_f32_dpp v116, v116, v116 row_mirror row_mask:0xf bank_mask:0xf bound_ctrl:1
	v_add_f32_dpp v137, v137, v137 row_mirror row_mask:0xf bank_mask:0xf bound_ctrl:1
	v_pk_fma_f32 v[112:113], v[116:117], v[52:53], v[112:113] op_sel_hi:[0,1,1] neg_lo:[1,0,0] neg_hi:[1,0,0]
	v_pk_fma_f32 v[114:115], v[116:117], v[54:55], v[114:115] op_sel_hi:[0,1,1] neg_lo:[1,0,0] neg_hi:[1,0,0]
	v_pk_fma_f32 v[0:1], v[0:1], v[40:41], v[112:113]
	v_pk_fma_f32 v[14:15], v[14:15], v[42:43], v[114:115]
	s_waitcnt lgkmcnt(5)
	ds_read_b128 v[36:39], v2 offset:38976
	ds_read_b128 v[40:43], v2 offset:40576
	ds_read_b128 v[44:47], v2 offset:40832
	ds_read_b128 v[48:51], v2 offset:41088
	ds_read_b128 v[52:55], v2 offset:41344
	v_pk_mul_f32 v[108:109], v[0:1], v[72:73]
	v_pk_mul_f32 v[110:111], v[0:1], v[60:61]
	v_pk_fma_f32 v[108:109], v[14:15], v[74:75], v[108:109]
	v_pk_fma_f32 v[110:111], v[14:15], v[62:63], v[110:111]
	v_add_f32_e32 v116, v108, v109
	v_add_f32_e32 v117, v110, v111
	v_pk_mul_f32 v[112:113], v[132:133], v[68:69] op_sel_hi:[0,1]
	v_add_f32_dpp v116, v116, v116 quad_perm:[1,0,3,2] row_mask:0xf bank_mask:0xf bound_ctrl:1
	v_add_f32_dpp v117, v117, v117 quad_perm:[1,0,3,2] row_mask:0xf bank_mask:0xf bound_ctrl:1
	v_pk_mul_f32 v[114:115], v[132:133], v[70:71] op_sel_hi:[0,1]
	v_add_f32_dpp v116, v116, v116 quad_perm:[2,3,0,1] row_mask:0xf bank_mask:0xf bound_ctrl:1
	v_add_f32_dpp v117, v117, v117 quad_perm:[2,3,0,1] row_mask:0xf bank_mask:0xf bound_ctrl:1
	v_cndmask_b32_e64 v118, v118, v137, s[34:35]
	v_add_f32_dpp v116, v116, v116 row_half_mirror row_mask:0xf bank_mask:0xf bound_ctrl:1
	v_add_f32_dpp v117, v117, v117 row_half_mirror row_mask:0xf bank_mask:0xf bound_ctrl:1
	s_nop 0
	v_add_f32_dpp v116, v116, v116 row_mirror row_mask:0xf bank_mask:0xf bound_ctrl:1
	v_add_f32_dpp v117, v117, v117 row_mirror row_mask:0xf bank_mask:0xf bound_ctrl:1
	v_pk_fma_f32 v[112:113], v[116:117], v[76:77], v[112:113] op_sel_hi:[0,1,1] neg_lo:[1,0,0] neg_hi:[1,0,0]
	v_pk_fma_f32 v[114:115], v[116:117], v[78:79], v[114:115] op_sel_hi:[0,1,1] neg_lo:[1,0,0] neg_hi:[1,0,0]
	v_pk_fma_f32 v[0:1], v[0:1], v[64:65], v[112:113]
	v_pk_fma_f32 v[14:15], v[14:15], v[66:67], v[114:115]
	s_waitcnt lgkmcnt(5)
	ds_read_b128 v[60:63], v2 offset:40320
	ds_read_b128 v[64:67], v2 offset:41920
	ds_read_b128 v[68:71], v2 offset:42176
	ds_read_b128 v[72:75], v2 offset:42432
	ds_read_b128 v[76:79], v2 offset:42688
	ds_read_b128 v[4:7], v2 offset:41664
	v_pk_mul_f32 v[108:109], v[0:1], v[96:97]
	v_pk_mul_f32 v[110:111], v[0:1], v[84:85]
	v_pk_fma_f32 v[108:109], v[14:15], v[98:99], v[108:109]
	v_pk_fma_f32 v[110:111], v[14:15], v[86:87], v[110:111]
	v_add_f32_e32 v116, v108, v109
	v_add_f32_e32 v137, v110, v111
	v_pk_mul_f32 v[112:113], v[132:133], v[92:93] op_sel:[1,0] op_sel_hi:[1,1]
	v_add_f32_dpp v116, v116, v116 quad_perm:[1,0,3,2] row_mask:0xf bank_mask:0xf bound_ctrl:1
	v_add_f32_dpp v137, v137, v137 quad_perm:[1,0,3,2] row_mask:0xf bank_mask:0xf bound_ctrl:1
	v_pk_mul_f32 v[114:115], v[132:133], v[94:95] op_sel:[1,0] op_sel_hi:[1,1]
	v_add_f32_dpp v116, v116, v116 quad_perm:[2,3,0,1] row_mask:0xf bank_mask:0xf bound_ctrl:1
	v_add_f32_dpp v137, v137, v137 quad_perm:[2,3,0,1] row_mask:0xf bank_mask:0xf bound_ctrl:1
	v_cndmask_b32_e64 v118, v118, v117, s[36:37]
	v_add_f32_dpp v116, v116, v116 row_half_mirror row_mask:0xf bank_mask:0xf bound_ctrl:1
	v_add_f32_dpp v137, v137, v137 row_half_mirror row_mask:0xf bank_mask:0xf bound_ctrl:1
	s_nop 0
	v_add_f32_dpp v116, v116, v116 row_mirror row_mask:0xf bank_mask:0xf bound_ctrl:1
	v_add_f32_dpp v137, v137, v137 row_mirror row_mask:0xf bank_mask:0xf bound_ctrl:1
	v_pk_fma_f32 v[112:113], v[116:117], v[100:101], v[112:113] op_sel_hi:[0,1,1] neg_lo:[1,0,0] neg_hi:[1,0,0]
	v_pk_fma_f32 v[114:115], v[116:117], v[102:103], v[114:115] op_sel_hi:[0,1,1] neg_lo:[1,0,0] neg_hi:[1,0,0]
	v_pk_fma_f32 v[0:1], v[0:1], v[88:89], v[112:113]
	v_pk_fma_f32 v[14:15], v[14:15], v[90:91], v[114:115]
	s_waitcnt lgkmcnt(6)
; __device__ __forceinline__ unsigned cvt_pk_bf16(float lo, float hi) { unsigned r; asm("v_cvt_pk_bf16_f32 %0, %1, %2" : "=v"(r) : "v"(lo), "v"(hi)); return r; }
; #define WKV_BAR() do { asm volatile("s_waitcnt lgkmcnt(0)" ::: "memory"); __builtin_amdgcn_s_barrier(); asm volatile("" ::: "memory"); } while (0)
; __device__ __forceinline__ void scan_wkv_prompt(PP P, int l, LAS unsigned char* lds, const Ids I) {
;     ...
;                     ykeep = (kseg == (s & 15)) ? y : ykeep;
;                     rp = r4; r4 = nr4; w4 = nw4; k4 = nk4; a4 = na4; b4 = nb4; vv = nvv;
;                     nr4 = mr4; nw4 = mw4; nk4 = mk4; na4 = ma4; nb4 = mb4; nvv = mvv;
;                     __builtin_amdgcn_sched_barrier(0);
;                     if ((s & 15) == 15) yb[((s & 16) + kseg) * 16 + wave * 4 + rowl] = ykeep;
;                 }
;             }
;             __builtin_amdgcn_s_setprio(0);
;             WKV_BAR();
;             { const int vrow = rg * 16 + wave * 4 + rowl; *(f32x4*)(out + O_PWKV + ((unsigned)((l * 8 + b) * 8 + h) * 64u + vrow) * 64u + kseg * 4) = (f32x4){S0, S1, S2, S3};
;               const float ylast = row16_allsum((S0 * rp[0] + S1 * rp[1]) + (S2 * rp[2] + S3 * rp[3]));
;               if (kseg == 0) ymix[(rowbase + 2047u) * 1024u + 512u + h * 64 + vrow] = (bf16_t)(cvt_pk_bf16(ylast, 0.f) & 0xffffu); }
	v_pk_mul_f32 v[108:109], v[0:1], v[48:49]
	v_pk_mul_f32 v[110:111], v[0:1], v[36:37]
	v_pk_fma_f32 v[108:109], v[14:15], v[50:51], v[108:109]
	v_pk_fma_f32 v[110:111], v[14:15], v[38:39], v[110:111]
	v_add_f32_e32 v116, v108, v109
	v_add_f32_e32 v117, v110, v111
	v_pk_mul_f32 v[112:113], v[134:135], v[44:45] op_sel_hi:[0,1]
	v_add_f32_dpp v116, v116, v116 quad_perm:[1,0,3,2] row_mask:0xf bank_mask:0xf bound_ctrl:1
	v_add_f32_dpp v117, v117, v117 quad_perm:[1,0,3,2] row_mask:0xf bank_mask:0xf bound_ctrl:1
	v_pk_mul_f32 v[114:115], v[134:135], v[46:47] op_sel_hi:[0,1]
	v_add_f32_dpp v116, v116, v116 quad_perm:[2,3,0,1] row_mask:0xf bank_mask:0xf bound_ctrl:1
	v_add_f32_dpp v117, v117, v117 quad_perm:[2,3,0,1] row_mask:0xf bank_mask:0xf bound_ctrl:1
	v_cndmask_b32_e64 v118, v118, v137, s[38:39]
	v_add_f32_dpp v116, v116, v116 row_half_mirror row_mask:0xf bank_mask:0xf bound_ctrl:1
	v_add_f32_dpp v117, v117, v117 row_half_mirror row_mask:0xf bank_mask:0xf bound_ctrl:1
	s_nop 0
	v_add_f32_dpp v116, v116, v116 row_mirror row_mask:0xf bank_mask:0xf bound_ctrl:1
	v_add_f32_dpp v117, v117, v117 row_mirror row_mask:0xf bank_mask:0xf bound_ctrl:1
	v_pk_fma_f32 v[112:113], v[116:117], v[52:53], v[112:113] op_sel_hi:[0,1,1] neg_lo:[1,0,0] neg_hi:[1,0,0]
	v_pk_fma_f32 v[114:115], v[116:117], v[54:55], v[114:115] op_sel_hi:[0,1,1] neg_lo:[1,0,0] neg_hi:[1,0,0]
	v_pk_fma_f32 v[0:1], v[0:1], v[40:41], v[112:113]
	v_pk_fma_f32 v[14:15], v[14:15], v[42:43], v[114:115]
	s_waitcnt lgkmcnt(1)
	v_pk_mul_f32 v[108:109], v[0:1], v[72:73]
	v_pk_mul_f32 v[110:111], v[0:1], v[60:61]
	v_pk_fma_f32 v[108:109], v[14:15], v[74:75], v[108:109]
	v_pk_fma_f32 v[110:111], v[14:15], v[62:63], v[110:111]
	v_add_f32_e32 v116, v108, v109
	v_add_f32_e32 v137, v110, v111
	v_pk_mul_f32 v[112:113], v[134:135], v[68:69] op_sel:[1,0] op_sel_hi:[1,1]
	v_add_f32_dpp v116, v116, v116 quad_perm:[1,0,3,2] row_mask:0xf bank_mask:0xf bound_ctrl:1
	v_add_f32_dpp v137, v137, v137 quad_perm:[1,0,3,2] row_mask:0xf bank_mask:0xf bound_ctrl:1
	v_pk_mul_f32 v[114:115], v[134:135], v[70:71] op_sel:[1,0] op_sel_hi:[1,1]
	v_add_f32_dpp v116, v116, v116 quad_perm:[2,3,0,1] row_mask:0xf bank_mask:0xf bound_ctrl:1
	v_add_f32_dpp v137, v137, v137 quad_perm:[2,3,0,1] row_mask:0xf bank_mask:0xf bound_ctrl:1
	v_cndmask_b32_e64 v118, v118, v117, s[40:41]
	v_add_f32_dpp v116, v116, v116 row_half_mirror row_mask:0xf bank_mask:0xf bound_ctrl:1
	v_add_f32_dpp v137, v137, v137 row_half_mirror row_mask:0xf bank_mask:0xf bound_ctrl:1
	s_nop 0
	v_add_f32_dpp v116, v116, v116 row_mirror row_mask:0xf bank_mask:0xf bound_ctrl:1
	v_add_f32_dpp v137, v137, v137 row_mirror row_mask:0xf bank_mask:0xf bound_ctrl:1
	v_pk_fma_f32 v[112:113], v[116:117], v[76:77], v[112:113] op_sel_hi:[0,1,1] neg_lo:[1,0,0] neg_hi:[1,0,0]
	v_pk_fma_f32 v[114:115], v[116:117], v[78:79], v[114:115] op_sel_hi:[0,1,1] neg_lo:[1,0,0] neg_hi:[1,0,0]
	v_pk_fma_f32 v[0:1], v[0:1], v[64:65], v[112:113]
	v_pk_fma_f32 v[14:15], v[14:15], v[66:67], v[114:115]
	v_cndmask_b32_e64 v118, v118, v137, s[42:43]
	ds_write_b32 v119, v118 offset:1024
	s_add_i32 s44, s44, 1
	s_cmp_eq_u32 s44, 64
	s_cbranch_scc0 .LBB0_760
	s_setprio 0
	s_lshl_b32 s44, s54, 3
	v_readlane_b32 s45, v254, 59
	v_lshl_add_u32 v16, s46, 4, v19
	s_add_i32 s44, s44, s45
	s_or_b32 s44, s44, s47
	v_lshlrev_b32_e32 v2, 6, v16
	v_lshl_add_u32 v144, s44, 12, v2
	v_lshl_add_u64 v[36:37], v[144:145], 2, v[10:11]
	v_mov_b32_e32 v2, v14
	v_mov_b32_e32 v3, v15
	s_waitcnt lgkmcnt(0)
	s_barrier
	global_store_dwordx4 v[36:37], v[0:3], off
	s_nop 1
	v_mul_f32_e32 v0, v4, v0
	v_fmac_f32_e32 v0, v5, v1
	v_mul_f32_e32 v1, v6, v14
	v_fmac_f32_e32 v1, v7, v15
	v_add_f32_e32 v0, v1, v0
	s_nop 1
	v_add_f32_dpp v0, v0, v0 quad_perm:[1,0,3,2] row_mask:0xf bank_mask:0xf bound_ctrl:1
	s_nop 1
	v_add_f32_dpp v0, v0, v0 quad_perm:[2,3,0,1] row_mask:0xf bank_mask:0xf bound_ctrl:1
	s_nop 1
	v_add_f32_dpp v0, v0, v0 row_half_mirror row_mask:0xf bank_mask:0xf bound_ctrl:1
	s_nop 1
	v_mov_b32_dpp v1, v0 row_mirror row_mask:0xf bank_mask:0xf bound_ctrl:1
	s_and_saveexec_b64 s[44:45], s[4:5]
	s_cbranch_execz .LBB0_763
	s_lshl_b32 s50, s54, 21
	s_lshl_b32 s51, s47, 6
	s_or_b32 s50, s50, s51
	v_add_u32_e32 v2, s50, v16
	v_add_u32_e32 v144, 0x1ffe00, v2
	v_lshl_add_u64 v[2:3], v[144:145], 1, s[78:79]
	v_add_f32_e32 v0, v0, v1
	v_cvt_pk_bf16_f32 v0, v0, v145
	global_store_short v[2:3], v0, off

; __device__ __forceinline__ void scan_wkv_prompt(PP P, int l, LAS unsigned char* lds, const Ids I) {
;     ...
;             WKV_DMA(0); WKV_DMA(1);
;             asm volatile("s_waitcnt vmcnt(6)" ::: "memory");
;             WKV_CONVERT(0);
.LBB0_764:
	s_and_b64 vcc, exec, s[44:45]
	s_cbranch_vccz .LBB0_757
	s_lshl_b32 s51, s54, 11
	v_add_u32_e32 v14, s51, v9
	s_lshl_b32 s50, s47, 6
	v_writelane_b32 v254, s54, 57
	v_lshlrev_b32_e32 v0, 9, v14
	v_or_b32_e32 v36, s50, v20
	v_or_b32_e32 v144, v36, v0
	v_readlane_b32 s66, v254, 35
	v_lshlrev_b64 v[2:3], 1, v[144:145]
	v_readlane_b32 s67, v254, 36
	v_readlane_b32 s76, v255, 0
	s_mov_b32 m0, s76
	v_lshl_add_u64 v[4:5], s[66:67], 0, v[2:3]
	v_readlane_b32 vcc_lo, v254, 37
	v_readlane_b32 s90, v254, 39
	global_load_lds_dwordx4 v[4:5], off
	v_lshl_add_u64 v[4:5], s[74:75], 0, v[2:3]
	s_add_i32 m0, s1, 0x17000
	v_readlane_b32 vcc_hi, v254, 38
	v_mov_b32_e32 v1, v145
	v_readlane_b32 s91, v254, 40
	global_load_lds_dwordx4 v[4:5], off
	v_lshl_add_u64 v[4:5], vcc, 0, v[2:3]
	s_add_i32 m0, s1, 0x18000
	v_lshl_add_u64 v[0:1], v[0:1], 1, s[90:91]
	s_lshl_b32 s54, s47, 7
	global_load_lds_dwordx4 v[4:5], off
	v_lshl_add_u64 v[4:5], s[52:53], 0, v[2:3]
	s_add_i32 m0, s1, 0x19000
	v_lshl_add_u64 v[0:1], v[0:1], 0, s[54:55]
	s_lshl_b32 s44, s46, 5
	s_mov_b32 s45, s55
	global_load_lds_dwordx4 v[4:5], off
	v_lshl_add_u64 v[2:3], s[70:71], 0, v[2:3]
	s_add_i32 m0, s1, 0x1a000
	v_lshl_add_u64 v[0:1], v[0:1], 0, s[44:45]
	v_lshlrev_b32_e32 v4, 1, v12
	v_mov_b32_e32 v5, v145
	v_readlane_b32 s47, v255, 2
	global_load_lds_dwordx4 v[2:3], off
	v_lshl_add_u64 v[0:1], v[0:1], 0, v[4:5]
	s_mov_b32 m0, s47
	s_nop 0
	global_load_lds_dword v[0:1], off
	v_add_lshl_u32 v0, v21, s51, 9
	v_or_b32_e32 v144, v36, v0
	v_lshlrev_b64 v[2:3], 1, v[144:145]
	v_lshl_add_u64 v[6:7], s[66:67], 0, v[2:3]
	s_add_i32 m0, s1, 0x1b400
	v_mov_b32_e32 v1, v145
	global_load_lds_dwordx4 v[6:7], off
	v_lshl_add_u64 v[6:7], s[74:75], 0, v[2:3]
	s_add_i32 m0, s1, 0x1c400
	v_lshl_add_u64 v[0:1], v[0:1], 1, s[90:91]
	global_load_lds_dwordx4 v[6:7], off
	v_lshl_add_u64 v[6:7], vcc, 0, v[2:3]
	s_add_i32 m0, s1, 0x1d400
	v_lshl_add_u64 v[0:1], v[0:1], 0, s[54:55]
	global_load_lds_dwordx4 v[6:7], off
	v_lshl_add_u64 v[6:7], s[52:53], 0, v[2:3]
	s_add_i32 m0, s1, 0x1e400
	v_lshl_add_u64 v[2:3], s[70:71], 0, v[2:3]
	global_load_lds_dwordx4 v[6:7], off
	s_add_i32 m0, s1, 0x1f400
	v_lshl_add_u64 v[0:1], v[0:1], 0, s[44:45]
	v_readlane_b32 s44, v255, 1
	global_load_lds_dwordx4 v[2:3], off
	v_lshl_add_u64 v[0:1], v[0:1], 0, v[4:5]
	s_add_i32 m0, s44, 0x20400
	s_nop 0
	global_load_lds_dword v[0:1], off
	s_waitcnt vmcnt(6)
	v_add_u32_e32 v0, s76, v22
	ds_read_b128 v[38:41], v0
	ds_read_b128 v[42:45], v0 offset:4096
	ds_read_b128 v[46:49], v0 offset:8192
	ds_read_b128 v[50:53], v0 offset:12288
	ds_read_b128 v[54:57], v0 offset:16384
	ds_read_b128 v[0:3], v35
	s_waitcnt lgkmcnt(0)
	v_lshlrev_b32_e32 v6, 16, v42
	v_lshlrev_b32_e32 v58, 16, v38
	v_and_b32_e32 v59, 0xffff0000, v38
	v_lshlrev_b32_e32 v60, 16, v39
	v_and_b32_e32 v61, 0xffff0000, v39
	v_lshlrev_b32_e32 v38, 16, v40
	v_and_b32_e32 v7, 0xffff0000, v42
	v_mul_f32_e32 v6, 0xbfb8aa3b, v6
	v_and_b32_e32 v39, 0xffff0000, v40
	v_lshlrev_b32_e32 v40, 16, v41
	v_and_b32_e32 v41, 0xffff0000, v41
	ds_write_b128 v23, v[58:61]
	ds_write_b128 v23, v[38:41] offset:16
	v_lshlrev_b32_e32 v15, 16, v43
	v_exp_f32_e32 v38, v6
	v_mul_f32_e32 v6, 0xbfb8aa3b, v7
	v_and_b32_e32 v16, 0xffff0000, v43
	v_exp_f32_e32 v39, v6
	v_mul_f32_e32 v6, 0xbfb8aa3b, v15
	v_exp_f32_e32 v40, v6
	v_mul_f32_e32 v6, 0xbfb8aa3b, v16
	v_exp_f32_e32 v41, v6
	v_lshlrev_b32_e32 v17, 16, v44
	v_and_b32_e32 v37, 0xffff0000, v44
	v_mul_f32_e32 v6, 0xbfb8aa3b, v17
	v_lshlrev_b32_e32 v42, 16, v45
	ds_write_b128 v23, v[38:41] offset:256
	v_exp_f32_e32 v38, v6
	v_mul_f32_e32 v6, 0xbfb8aa3b, v37
	v_and_b32_e32 v43, 0xffff0000, v45
	v_exp_f32_e32 v39, v6
	v_mul_f32_e32 v6, 0xbfb8aa3b, v42
	v_exp_f32_e32 v40, v6
	v_mul_f32_e32 v6, 0xbfb8aa3b, v43
	v_exp_f32_e32 v41, v6
	v_lshlrev_b32_e32 v42, 16, v48
	v_and_b32_e32 v43, 0xffff0000, v48
	v_lshlrev_b32_e32 v44, 16, v49
	ds_write_b128 v23, v[38:41] offset:272
	v_lshlrev_b32_e32 v38, 16, v46
	v_and_b32_e32 v39, 0xffff0000, v46
	v_lshlrev_b32_e32 v40, 16, v47
	v_and_b32_e32 v41, 0xffff0000, v47
	v_and_b32_e32 v45, 0xffff0000, v49
	ds_write_b128 v23, v[38:41] offset:512
	ds_write_b128 v23, v[42:45] offset:528
	v_lshlrev_b32_e32 v38, 16, v50
	v_and_b32_e32 v39, 0xffff0000, v50
	v_lshlrev_b32_e32 v40, 16, v51
	v_and_b32_e32 v41, 0xffff0000, v51
	v_lshlrev_b32_e32 v42, 16, v52
	v_and_b32_e32 v43, 0xffff0000, v52
	v_lshlrev_b32_e32 v44, 16, v53
	v_and_b32_e32 v45, 0xffff0000, v53
	ds_write_b128 v23, v[38:41] offset:768
	ds_write_b128 v23, v[42:45] offset:784
	v_lshlrev_b32_e32 v38, 16, v54
	v_and_b32_e32 v39, 0xffff0000, v54
	v_lshlrev_b32_e32 v40, 16, v55
	v_and_b32_e32 v41, 0xffff0000, v55
	v_lshlrev_b32_e32 v42, 16, v56
	v_and_b32_e32 v43, 0xffff0000, v56
	v_lshlrev_b32_e32 v44, 16, v57
	v_and_b32_e32 v45, 0xffff0000, v57
	ds_write_b128 v23, v[38:41] offset:1024
	ds_write_b128 v23, v[42:45] offset:1040
	s_and_saveexec_b64 s[44:45], s[6:7]
	s_cbranch_execz .LBB0_767
	v_lshlrev_b32_e32 v38, 16, v0
	v_and_b32_e32 v39, 0xffff0000, v0
	v_lshlrev_b32_e32 v40, 16, v1
	v_and_b32_e32 v41, 0xffff0000, v1
	v_lshlrev_b32_e32 v0, 16, v2
	v_and_b32_e32 v1, 0xffff0000, v2
	v_lshlrev_b32_e32 v2, 16, v3
	v_and_b32_e32 v3, 0xffff0000, v3
	ds_write_b32 v124, v38
	ds_write_b32 v124, v39 offset:128
	ds_write_b32 v124, v40 offset:256
	ds_write_b32 v124, v41 offset:384
	ds_write_b32 v124, v0 offset:512
	ds_write_b32 v124, v1 offset:640
	ds_write_b32 v124, v2 offset:768
	ds_write_b32 v124, v3 offset:896

.LBB0_773:
	s_and_b32 s44, s67, 1
	s_mul_i32 s45, s44, 0x5400
	s_add_i32 s45, s45, 0
	s_add_i32 s45, s45, 0x16000
	s_add_i32 s46, s45, s0
	v_add_u32_e32 v0, s46, v22
	ds_read_b128 v[60:63], v0
	ds_read_b128 v[64:67], v0 offset:4096
	ds_read_b128 v[68:71], v0 offset:8192
	ds_read_b128 v[72:75], v0 offset:12288
	ds_read_b128 v[76:79], v0 offset:16384
	s_mul_i32 s44, s44, 0xa800
	s_add_i32 s45, s45, s57
	v_add_u32_e32 v58, s44, v23
	v_add3_u32 v0, s45, v24, v25
	s_waitcnt lgkmcnt(0)
	v_lshlrev_b32_e32 v80, 16, v60
	v_and_b32_e32 v81, 0xffff0000, v60
	v_lshlrev_b32_e32 v82, 16, v61
	v_and_b32_e32 v83, 0xffff0000, v61
	v_and_b32_e32 v61, 0xffff0000, v62
	v_lshlrev_b32_e32 v59, 16, v64
	ds_read_b128 v[0:3], v0 offset:20480
	v_lshlrev_b32_e32 v60, 16, v62
	v_lshlrev_b32_e32 v62, 16, v63
	v_and_b32_e32 v63, 0xffff0000, v63
	ds_write_b128 v58, v[80:83]
	ds_write_b128 v58, v[60:63] offset:16
	v_and_b32_e32 v61, 0xffff0000, v64
	v_mul_f32_e32 v59, 0xbfb8aa3b, v59
	v_lshlrev_b32_e32 v62, 16, v65
	v_exp_f32_e32 v60, v59
	v_mul_f32_e32 v59, 0xbfb8aa3b, v61
	v_and_b32_e32 v63, 0xffff0000, v65
	v_exp_f32_e32 v61, v59
	v_mul_f32_e32 v59, 0xbfb8aa3b, v62
	v_exp_f32_e32 v62, v59
	v_mul_f32_e32 v59, 0xbfb8aa3b, v63
	v_exp_f32_e32 v63, v59
	v_lshlrev_b32_e32 v64, 16, v66
	v_and_b32_e32 v65, 0xffff0000, v66
	v_mul_f32_e32 v59, 0xbfb8aa3b, v64
	v_lshlrev_b32_e32 v66, 16, v67
	ds_write_b128 v58, v[60:63] offset:256
	v_exp_f32_e32 v60, v59
	v_mul_f32_e32 v59, 0xbfb8aa3b, v65
	v_and_b32_e32 v67, 0xffff0000, v67
	v_exp_f32_e32 v61, v59
	v_mul_f32_e32 v59, 0xbfb8aa3b, v66
	v_exp_f32_e32 v62, v59
	v_mul_f32_e32 v59, 0xbfb8aa3b, v67
	v_exp_f32_e32 v63, v59
	v_lshlrev_b32_e32 v64, 16, v70
	v_and_b32_e32 v65, 0xffff0000, v70
	v_lshlrev_b32_e32 v66, 16, v71
	ds_write_b128 v58, v[60:63] offset:272
	v_lshlrev_b32_e32 v60, 16, v68
	v_and_b32_e32 v61, 0xffff0000, v68
	v_lshlrev_b32_e32 v62, 16, v69
	v_and_b32_e32 v63, 0xffff0000, v69
	v_and_b32_e32 v67, 0xffff0000, v71
	ds_write_b128 v58, v[60:63] offset:512
	ds_write_b128 v58, v[64:67] offset:528
	v_lshlrev_b32_e32 v60, 16, v72
	v_and_b32_e32 v61, 0xffff0000, v72
	v_lshlrev_b32_e32 v62, 16, v73
	v_and_b32_e32 v63, 0xffff0000, v73
	v_lshlrev_b32_e32 v64, 16, v74
	v_and_b32_e32 v65, 0xffff0000, v74
	v_lshlrev_b32_e32 v66, 16, v75
	v_and_b32_e32 v67, 0xffff0000, v75
	ds_write_b128 v58, v[60:63] offset:768
	ds_write_b128 v58, v[64:67] offset:784
	v_lshlrev_b32_e32 v60, 16, v76
	v_and_b32_e32 v61, 0xffff0000, v76
	v_lshlrev_b32_e32 v62, 16, v77
	v_and_b32_e32 v63, 0xffff0000, v77
	v_lshlrev_b32_e32 v64, 16, v78
	v_and_b32_e32 v65, 0xffff0000, v78
	v_lshlrev_b32_e32 v66, 16, v79
	v_and_b32_e32 v67, 0xffff0000, v79
	ds_write_b128 v58, v[60:63] offset:1024
	ds_write_b128 v58, v[64:67] offset:1040
	s_and_saveexec_b64 s[44:45], s[6:7]
	s_cbranch_execz .LBB0_775
	s_waitcnt lgkmcnt(0)
	v_lshlrev_b32_e32 v60, 16, v0
	v_and_b32_e32 v61, 0xffff0000, v0
	v_lshlrev_b32_e32 v62, 16, v1
	v_and_b32_e32 v63, 0xffff0000, v1
	v_lshlrev_b32_e32 v0, 16, v2
	v_and_b32_e32 v1, 0xffff0000, v2
	v_lshlrev_b32_e32 v2, 16, v3
	v_and_b32_e32 v3, 0xffff0000, v3
	s_and_b32 s100, s67, 1
	s_lshl_b32 s100, s100, 11
	v_add_u32_e32 v125, s100, v124
	ds_write_b32 v125, v60
	ds_write_b32 v125, v61 offset:128
	ds_write_b32 v125, v62 offset:256
	ds_write_b32 v125, v63 offset:384
	ds_write_b32 v125, v0 offset:512
	ds_write_b32 v125, v1 offset:640
	ds_write_b32 v125, v2 offset:768
	ds_write_b32 v125, v3 offset:896

; __device__ __forceinline__ void scan_wkv_prompt(PP P, int l, LAS unsigned char* lds, const Ids I) {
;     ...
;                 asm volatile("s_waitcnt vmcnt(0)" ::: "memory");
;                 const unsigned lr = lrow0 + (unsigned)(c & 31) * 4u; bf16_t vla[4], vgx[4], vgb[4];
; #pragma unroll
;                 for (int k = 0; k < 4; ++k) { vla[k] = LAp[(lr + k) * 512u + lch]; vgx[k] = GXp[(lr + k) * 512u + lch]; vgb[k] = PRp[(lr + k) * (unsigned)INW + 512u + lch]; }
.LBB0_780:
	s_waitcnt lgkmcnt(0)
	s_cmp_eq_u32 s66, 0
	s_cbranch_scc1 .Lldr_wall
	s_cmp_gt_u32 s66, 61
	s_cbranch_scc1 .Lldr_wall
	s_waitcnt vmcnt(7)
	s_branch .Lldr_wdone

; __device__ __forceinline__ float bf2f(bf16_t h) { return __uint_as_float((unsigned)h << 16); }
; __device__ __forceinline__ bf16_t f2bf(float f) { return (bf16_t)(cvt_pk_bf16(f, 0.f) & 0xffffu); }
; __device__ __forceinline__ float gelu_tanh(float x) { const float u = 0.7978845608f * (x + 0.044715f * x * x * x); return 0.5f * x * (1.0f + tanh_f(u)); }
; __device__ __forceinline__ void scan_wkv_prompt(PP P, int l, LAS unsigned char* lds, const Ids I) {
;     ...
;                 for (int k = 0; k < 4; ++k) { const float la = bf2f(vla[k]), gx = bf2f(vgx[k]); const float a = __expf(la), bb = sqrtf(fmaxf(1.f - a * a, 0.f)) * gx;
;                     if (c < 32) { lB = a * lB + bb; lA *= a; }
;                     else { lh = a * lh + bb; ymix[(lr + k) * 1024u + lch] = f2bf(lh * gelu_tanh(bf2f(vgb[k]))); } }
.Lldr_wdone:
	v_lshlrev_b32_e32 v0, 16, v57
	v_mul_f32_e32 v0, 0x3fb8aa3b, v0
	v_exp_f32_e32 v1, v0
	v_lshlrev_b32_e32 v3, 16, v56
	s_cmp_gt_u32 s66, 31
	s_cselect_b64 s[46:47], -1, 0
	v_fma_f32 v0, -v1, v1, 1.0
	v_max_f32_e32 v0, 0, v0
	v_mul_f32_e32 v2, 0x4f800000, v0
	v_cmp_gt_f32_e32 vcc, s90, v0
	s_nop 1
	v_cndmask_b32_e32 v0, v0, v2, vcc
	v_sqrt_f32_e32 v2, v0
	s_nop 0
	v_add_u32_e32 v56, -1, v2
	v_fma_f32 v58, -v56, v2, v0
	v_add_u32_e32 v57, 1, v2
	v_cmp_ge_f32_e64 s[44:45], 0, v58
	s_nop 1
	v_cndmask_b32_e64 v56, v2, v56, s[44:45]
	v_fma_f32 v2, -v57, v2, v0
	v_cmp_lt_f32_e64 s[44:45], 0, v2
	s_nop 1
	v_cndmask_b32_e64 v2, v56, v57, s[44:45]
	v_mul_f32_e32 v56, 0x37800000, v2
	v_cndmask_b32_e32 v2, v2, v56, vcc
	v_cmp_class_f32_e32 vcc, v0, v175
	s_mov_b64 s[44:45], -1
	s_nop 0
	v_cndmask_b32_e32 v0, v2, v0, vcc
	v_mul_f32_e32 v2, v0, v3
	s_and_b64 vcc, exec, s[46:47]
	s_cbranch_vccz .LBB0_782
	v_lshlrev_b32_e32 v0, 16, v55
	v_mul_f32_e32 v3, 0x3d372713, v0
	v_mul_f32_e32 v3, v3, v0
	v_fma_f32 v3, v3, v0, v0
	v_mul_f32_e32 v3, 0x3f4c422a, v3
	v_add_f32_e32 v3, v3, v3
	v_mul_f32_e32 v3, 0x3fb8aa3b, v3
	v_exp_f32_e32 v3, v3
	v_pk_mul_f32 v[56:57], v[0:1], v[146:147]
	v_lshl_or_b32 v144, v5, 10, v37
	v_add_f32_e32 v0, v2, v57
	v_add_f32_e32 v3, 1.0, v3
	v_rcp_f32_e32 v3, v3
	s_mov_b64 s[44:45], 0
	v_fma_f32 v3, v3, -2.0, 1.0
	v_add_f32_e32 v3, 1.0, v3
	v_mul_f32_e32 v3, v3, v56
	v_mul_f32_e32 v3, v3, v0
	v_lshl_add_u64 v[56:57], v[144:145], 1, s[78:79]
	v_cvt_pk_bf16_f32 v3, v3, v145
	global_store_short v[56:57], v3, off

; __global__ void __launch_bounds__(512) mega(Params Pval) {
	.amdhsa_kernel _Z4mega6Params
		.amdhsa_group_segment_fixed_size 0
		.amdhsa_private_segment_fixed_size 0
		.amdhsa_kernarg_size 592
		.amdhsa_user_sgpr_count 2
		.amdhsa_user_sgpr_dispatch_ptr 0
		.amdhsa_user_sgpr_queue_ptr 0
		.amdhsa_user_sgpr_kernarg_segment_ptr 1
		.amdhsa_user_sgpr_dispatch_id 0
		.amdhsa_user_sgpr_kernarg_preload_length 0
		.amdhsa_user_sgpr_kernarg_preload_offset 0
		.amdhsa_user_sgpr_private_segment_size 0
		.amdhsa_uses_dynamic_stack 0
		.amdhsa_enable_private_segment 0
		.amdhsa_system_sgpr_workgroup_id_x 1
		.amdhsa_system_sgpr_workgroup_id_y 0
		.amdhsa_system_sgpr_workgroup_id_z 0
		.amdhsa_system_sgpr_workgroup_info 0
		.amdhsa_system_vgpr_workitem_id 2
		.amdhsa_next_free_vgpr 256
		.amdhsa_next_free_sgpr 101
		.amdhsa_accum_offset 256
		.amdhsa_reserve_vcc 1
		.amdhsa_float_round_mode_32 0
		.amdhsa_float_round_mode_16_64 0
		.amdhsa_float_denorm_mode_32 3
		.amdhsa_float_denorm_mode_16_64 3
		.amdhsa_dx10_clamp 1
		.amdhsa_ieee_mode 1
		.amdhsa_fp16_overflow 0
		.amdhsa_tg_split 0
		.amdhsa_exception_fp_ieee_invalid_op 0
		.amdhsa_exception_fp_denorm_src 0
		.amdhsa_exception_fp_ieee_div_zero 0
		.amdhsa_exception_fp_ieee_overflow 0
		.amdhsa_exception_fp_ieee_underflow 0
		.amdhsa_exception_fp_ieee_inexact 0
		.amdhsa_exception_int_div_zero 0
	.end_amdhsa_kernel

; __global__ void __launch_bounds__(512) mega(Params Pval) {
amdhsa.kernels:
  - .agpr_count:     0
    .args:
      - .offset:         0
        .size:           336
        .value_kind:     by_value
      - .offset:         336
        .size:           4
        .value_kind:     hidden_block_count_x
      - .offset:         340
        .size:           4
        .value_kind:     hidden_block_count_y
      - .offset:         344
        .size:           4
        .value_kind:     hidden_block_count_z
      - .offset:         348
        .size:           2
        .value_kind:     hidden_group_size_x
      - .offset:         350
        .size:           2
        .value_kind:     hidden_group_size_y
      - .offset:         352
        .size:           2
        .value_kind:     hidden_group_size_z
      - .offset:         354
        .size:           2
        .value_kind:     hidden_remainder_x
      - .offset:         356
        .size:           2
        .value_kind:     hidden_remainder_y
      - .offset:         358
        .size:           2
        .value_kind:     hidden_remainder_z
      - .offset:         376
        .size:           8
        .value_kind:     hidden_global_offset_x
      - .offset:         384
        .size:           8
        .value_kind:     hidden_global_offset_y
      - .offset:         392
        .size:           8
        .value_kind:     hidden_global_offset_z
      - .offset:         400
        .size:           2
        .value_kind:     hidden_grid_dims
      - .offset:         424
        .size:           8
        .value_kind:     hidden_multigrid_sync_arg
      - .offset:         456
        .size:           4
        .value_kind:     hidden_dynamic_lds_size
    .group_segment_fixed_size: 0
    .kernarg_segment_align: 8
    .kernarg_segment_size: 592
    .language:       OpenCL C
    .language_version:
      - 2
      - 0
    .max_flat_workgroup_size: 512
    .name:           _Z4mega6Params
    .private_segment_fixed_size: 0
    .sgpr_count:     107
    .sgpr_spill_count: 92
    .symbol:         _Z4mega6Params.kd
    .uniform_work_group_size: 1
    .uses_dynamic_stack: false
    .vgpr_count:     256
    .vgpr_spill_count: 0
    .wavefront_size: 64
